# P4: residual x-tile loads streamed through the K-loop (acc starts at 0, 4 loads+16 adds per iteration, vmcnt recounted); P3: redundant in-loop vmcnt(0) removed
# speedup vs baseline: 1.0037x; 1.0037x over previous
; #define PG8_STAGE(bufoff, gbase, voff) do { _Pragma("unroll") for (int _i = 0; _i < 2; ++_i) \
;         __builtin_amdgcn_global_load_lds((const unsigned*)((const char*)(gbase) + (voff)[_i]), (PG8_LAS unsigned*)(lds + (bufoff) + ldsw + _i * 8192), 16, 0, 0); } while (0)
; #define PG8_LDA(dst, b, h) do { _Pragma("unroll") for (int m = 0; m < 4; ++m) _Pragma("unroll") for (int k = 0; k < 2; ++k) dst[m][k] = *(const PG8_LAS bf16x8*)(lds + PG8_SA(b, h) + aoff + m * 2048 + k * 1024); } while (0)
; #define PG8_WAIT_V(n) asm volatile("s_waitcnt vmcnt(" #n ")" ::: "memory")
; #define PG8_BAR __builtin_amdgcn_s_barrier()
; template <class Epi, class Sched, bool ALIGN_EPI = false, bool SP2 = false>
; __device__ __forceinline__ void gemm_phase(PG8_LAS unsigned char* lds, const Gemm g, const Sched& S, const Epi& E) {
;     ...
;         for (int t = 0; t < nt; t += 2) {
;             if constexpr (Epi::HAS_MID) { if (t == nt / 2) E.mid(acc, cur, wr, wc, fr, fq); }
;             const bool last = (t == nt - 2);
;             const char* a1 = cA + (size_t)(t + 1) * kstep;
;             const char* a2 = last ? nA : cA + (size_t)(t + 2) * kstep; const char* b2 = last ? nB : cB + (size_t)(t + 2) * kstep;
;             const char* a3 = a2 + kstep; const char* b3 = b2 + kstep;
;             if (last && has_next) S.a_ready(nxt);
;             if constexpr (SP2) {
;             PG8_LDB(B0, 0, 0); PG8_LDB(B1, 0, 1); PG8_SCHED; PG8_LDA(At, 0, 0); PG8_STAGE(PG8_SA(1, 1), a1 + hstep, voffA);
;             PG8_WAIT_V(8); PG8_WAIT_L(0); PG8_BAR; PG8_MMA(0, 0, At, B0); PG8_MMA(0, 1, At, B1); PG8_BAR; PG8_SCHED;
;             PG8_LDA(At, 0, 1); PG8_STAGE(PG8_SB(0, 0), b2, voffB); PG8_STAGE(PG8_SB(0, 1), b2 + hstep, voffB); PG8_STAGE(PG8_SA(0, 0), a2, voffA);
;             PG8_WAIT_V(8); PG8_WAIT_L(0); PG8_BAR; PG8_MMA(1, 0, At, B0); PG8_MMA(1, 1, At, B1); PG8_BAR; PG8_SCHED;
;             PG8_LDB(B0, 1, 0); PG8_LDB(B1, 1, 1); PG8_SCHED; PG8_LDA(At, 1, 0); PG8_STAGE(PG8_SA(0, 1), a2 + hstep, voffA);
;             PG8_WAIT_V(8); PG8_WAIT_L(0); PG8_BAR; PG8_MMA(0, 0, At, B0); PG8_MMA(0, 1, At, B1); PG8_BAR; PG8_SCHED;
;             PG8_LDA(At, 1, 1); PG8_STAGE(PG8_SB(1, 0), b3, voffB); PG8_STAGE(PG8_SB(1, 1), b3 + hstep, voffB); PG8_STAGE(PG8_SA(1, 0), a3, voffA);
;             PG8_WAIT_V(8); PG8_WAIT_L(0); PG8_BAR; PG8_MMA(1, 0, At, B0); PG8_MMA(1, 1, At, B1); PG8_BAR; PG8_SCHED;
.LBB0_587:
	s_add_u32 s2, s46, s60
	s_addc_u32 s62, s47, s61
	s_add_u32 s2, s2, 0x100
	s_addc_u32 s62, s62, 0
	s_add_u32 s95, s92, s60
	s_addc_u32 s63, s93, s61
	s_add_i32 s96, 0, 0x10000
	v_add_u32_e32 v3, s96, v209
	ds_read_b128 v[134:137], v3
	ds_read_b128 v[138:141], v3 offset:1024
	ds_read_b128 v[142:145], v3 offset:2048
	ds_read_b128 v[146:149], v3 offset:3072
	v_add_u32_e32 v3, s88, v209
	ds_read_b128 v[150:153], v3
	ds_read_b128 v[154:157], v3 offset:1024
	ds_read_b128 v[158:161], v3 offset:2048
	ds_read_b128 v[162:165], v3 offset:3072
	s_cmpk_eq_i32 s60, 0x700
	s_cselect_b32 s65, s29, s62
	s_cselect_b32 s64, s90, s2
	s_cselect_b32 s63, s31, s63
	s_cselect_b32 s62, s91, s95
	v_lshl_add_u64 v[4:5], v[204:205], 0, s[60:61]
	s_add_i32 m0, s59, 0xc000
	ds_read_b128 v[166:169], v210
	ds_read_b128 v[170:173], v210 offset:1024
	ds_read_b128 v[174:177], v210 offset:2048
	ds_read_b128 v[178:181], v210 offset:3072
	ds_read_b128 v[182:185], v210 offset:4096
	ds_read_b128 v[186:189], v210 offset:5120
	ds_read_b128 v[212:215], v210 offset:6144
	ds_read_b128 v[216:219], v210 offset:7168
	global_load_lds_dwordx4 v[4:5], off
	v_lshl_add_u64 v[4:5], v[206:207], 0, s[60:61]
	s_add_i32 m0, s59, 0xe000
	s_nop 0
	global_load_lds_dwordx4 v[4:5], off
	s_waitcnt vmcnt(8)
	s_waitcnt lgkmcnt(0)
	s_barrier
	s_setprio 1
	s_waitcnt lgkmcnt(0)
	v_mfma_f32_16x16x32_bf16 v[130:133], v[134:137], v[166:169], v[130:133]
	v_mfma_f32_16x16x32_bf16 v[126:129], v[142:145], v[166:169], v[126:129]
	v_mfma_f32_16x16x32_bf16 v[114:117], v[134:137], v[174:177], v[114:117]
	v_mfma_f32_16x16x32_bf16 v[110:113], v[142:145], v[174:177], v[110:113]
	v_mfma_f32_16x16x32_bf16 v[98:101], v[134:137], v[182:185], v[98:101]
	v_mfma_f32_16x16x32_bf16 v[94:97], v[142:145], v[182:185], v[94:97]
	v_mfma_f32_16x16x32_bf16 v[82:85], v[134:137], v[212:215], v[82:85]
	v_mfma_f32_16x16x32_bf16 v[78:81], v[142:145], v[212:215], v[78:81]
	v_mfma_f32_16x16x32_bf16 v[130:133], v[138:141], v[170:173], v[130:133]
	v_mfma_f32_16x16x32_bf16 v[126:129], v[146:149], v[170:173], v[126:129]
	v_mfma_f32_16x16x32_bf16 v[114:117], v[138:141], v[178:181], v[114:117]
	v_mfma_f32_16x16x32_bf16 v[110:113], v[146:149], v[178:181], v[110:113]
	v_mfma_f32_16x16x32_bf16 v[98:101], v[138:141], v[186:189], v[98:101]
	v_mfma_f32_16x16x32_bf16 v[94:97], v[146:149], v[186:189], v[94:97]
	v_mfma_f32_16x16x32_bf16 v[82:85], v[138:141], v[216:219], v[82:85]
	v_mfma_f32_16x16x32_bf16 v[78:81], v[146:149], v[216:219], v[78:81]
	s_setprio 0
	s_setprio 1
	v_mfma_f32_16x16x32_bf16 v[122:125], v[150:153], v[166:169], v[122:125]
	v_mfma_f32_16x16x32_bf16 v[118:121], v[158:161], v[166:169], v[118:121]
	v_mfma_f32_16x16x32_bf16 v[106:109], v[150:153], v[174:177], v[106:109]
	v_mfma_f32_16x16x32_bf16 v[102:105], v[158:161], v[174:177], v[102:105]
	v_mfma_f32_16x16x32_bf16 v[90:93], v[150:153], v[182:185], v[90:93]
	v_mfma_f32_16x16x32_bf16 v[86:89], v[158:161], v[182:185], v[86:89]
	v_mfma_f32_16x16x32_bf16 v[74:77], v[150:153], v[212:215], v[74:77]
	v_mfma_f32_16x16x32_bf16 v[70:73], v[158:161], v[212:215], v[70:73]
	v_mfma_f32_16x16x32_bf16 v[122:125], v[154:157], v[170:173], v[122:125]
	v_mfma_f32_16x16x32_bf16 v[118:121], v[162:165], v[170:173], v[118:121]
	v_mfma_f32_16x16x32_bf16 v[106:109], v[154:157], v[178:181], v[106:109]
	v_mfma_f32_16x16x32_bf16 v[102:105], v[162:165], v[178:181], v[102:105]
	v_mfma_f32_16x16x32_bf16 v[90:93], v[154:157], v[186:189], v[90:93]
	v_mfma_f32_16x16x32_bf16 v[86:89], v[162:165], v[186:189], v[86:89]
	v_mfma_f32_16x16x32_bf16 v[74:77], v[154:157], v[216:219], v[74:77]
	v_mfma_f32_16x16x32_bf16 v[70:73], v[162:165], v[216:219], v[70:73]
	s_setprio 0
	s_barrier
	s_add_i32 s2, s96, s58
	v_lshl_add_u64 v[220:221], s[62:63], 0, v[192:193]
	s_mov_b32 m0, s2
	ds_read_b128 v[166:169], v210 offset:16384
	ds_read_b128 v[170:173], v210 offset:17408
	ds_read_b128 v[174:177], v210 offset:18432
	ds_read_b128 v[178:181], v210 offset:19456
	ds_read_b128 v[182:185], v210 offset:20480
	ds_read_b128 v[186:189], v210 offset:21504
	ds_read_b128 v[212:215], v210 offset:22528
	ds_read_b128 v[216:219], v210 offset:23552
	global_load_lds_dwordx4 v[220:221], off
	s_add_i32 m0, s2, 0x2000
	s_add_u32 s96, s62, 0x40000
	v_lshl_add_u64 v[222:223], s[62:63], 0, v[196:197]
	s_addc_u32 s97, s63, 0
	s_add_i32 s2, s88, s58
	global_load_lds_dwordx4 v[222:223], off
	v_lshl_add_u64 v[4:5], s[96:97], 0, v[192:193]
	s_mov_b32 m0, s2
	v_lshl_add_u64 v[224:225], s[64:65], 0, v[190:191]
	global_load_lds_dwordx4 v[4:5], off
	v_lshl_add_u64 v[4:5], s[96:97], 0, v[196:197]
	s_add_i32 m0, s2, 0x2000
	v_lshl_add_u64 v[226:227], s[64:65], 0, v[194:195]
	global_load_lds_dwordx4 v[4:5], off
	s_mov_b32 m0, s59
	s_nop 0
	global_load_lds_dwordx4 v[224:225], off
	s_mov_b32 m0, s66
	s_nop 0
	global_load_lds_dwordx4 v[226:227], off
	s_waitcnt vmcnt(8)
	s_waitcnt lgkmcnt(0)
	s_barrier
; #define PG8_STAGE(bufoff, gbase, voff) do { _Pragma("unroll") for (int _i = 0; _i < 2; ++_i) \
;         __builtin_amdgcn_global_load_lds((const unsigned*)((const char*)(gbase) + (voff)[_i]), (PG8_LAS unsigned*)(lds + (bufoff) + ldsw + _i * 8192), 16, 0, 0); } while (0)
; #define PG8_LDA(dst, b, h) do { _Pragma("unroll") for (int m = 0; m < 4; ++m) _Pragma("unroll") for (int k = 0; k < 2; ++k) dst[m][k] = *(const PG8_LAS bf16x8*)(lds + PG8_SA(b, h) + aoff + m * 2048 + k * 1024); } while (0)
; #define PG8_LDB(dst, b, h) do { _Pragma("unroll") for (int n = 0; n < 2; ++n) _Pragma("unroll") for (int k = 0; k < 2; ++k) dst[n][k] = *(const PG8_LAS bf16x8*)(lds + PG8_SB(b, h) + boff + n * 2048 + k * 1024); } while (0)
; #define PG8_MMA(ai, bj, At, Bt) do { __builtin_amdgcn_s_setprio(1); _Pragma("unroll") for (int m = 0; m < 4; ++m) _Pragma("unroll") for (int n = 0; n < 2; ++n) _Pragma("unroll") for (int k = 0; k < 2; ++k) \
;         acc[ai][bj][m][n] = __builtin_amdgcn_mfma_f32_16x16x32_bf16(Bt[n][k], At[m][k], acc[ai][bj][m][n], 0, 0, 0); __builtin_amdgcn_s_setprio(0); } while (0)
; #define PG8_WAIT_V(n) asm volatile("s_waitcnt vmcnt(" #n ")" ::: "memory")
; #define PG8_WAIT_L(n) asm volatile("s_waitcnt lgkmcnt(" #n ")" ::: "memory")
; #define PG8_BAR __builtin_amdgcn_s_barrier()
; #define PG8_SCHED __builtin_amdgcn_sched_barrier(0)
; template <class Epi, class Sched, bool ALIGN_EPI = false, bool SP2 = false>
; __device__ __forceinline__ void gemm_phase(PG8_LAS unsigned char* lds, const Gemm g, const Sched& S, const Epi& E) {
;     ...
;             PG8_WAIT_V(8); PG8_WAIT_L(0); PG8_BAR; PG8_MMA(1, 0, At, B0); PG8_MMA(1, 1, At, B1); PG8_BAR; PG8_SCHED;
;             PG8_LDB(B0, 1, 0); PG8_LDB(B1, 1, 1); PG8_SCHED; PG8_LDA(At, 1, 0); PG8_STAGE(PG8_SA(0, 1), a2 + hstep, voffA);
;             PG8_WAIT_V(8); PG8_WAIT_L(0); PG8_BAR; PG8_MMA(0, 0, At, B0); PG8_MMA(0, 1, At, B1); PG8_BAR; PG8_SCHED;
;             PG8_LDA(At, 1, 1); PG8_STAGE(PG8_SB(1, 0), b3, voffB); PG8_STAGE(PG8_SB(1, 1), b3 + hstep, voffB); PG8_STAGE(PG8_SA(1, 0), a3, voffA);
;             PG8_WAIT_V(8); PG8_WAIT_L(0); PG8_BAR; PG8_MMA(1, 0, At, B0); PG8_MMA(1, 1, At, B1); PG8_BAR; PG8_SCHED;
	s_setprio 1
	s_waitcnt lgkmcnt(0)
	v_mfma_f32_16x16x32_bf16 v[66:69], v[134:137], v[166:169], v[66:69]
	v_mfma_f32_16x16x32_bf16 v[62:65], v[142:145], v[166:169], v[62:65]
	v_mfma_f32_16x16x32_bf16 v[50:53], v[134:137], v[174:177], v[50:53]
	v_mfma_f32_16x16x32_bf16 v[46:49], v[142:145], v[174:177], v[46:49]
	v_mfma_f32_16x16x32_bf16 v[34:37], v[134:137], v[182:185], v[34:37]
	v_mfma_f32_16x16x32_bf16 v[30:33], v[142:145], v[182:185], v[30:33]
	v_mfma_f32_16x16x32_bf16 v[18:21], v[134:137], v[212:215], v[18:21]
	v_mfma_f32_16x16x32_bf16 v[14:17], v[142:145], v[212:215], v[14:17]
	v_mfma_f32_16x16x32_bf16 v[66:69], v[138:141], v[170:173], v[66:69]
	v_mfma_f32_16x16x32_bf16 v[62:65], v[146:149], v[170:173], v[62:65]
	v_mfma_f32_16x16x32_bf16 v[50:53], v[138:141], v[178:181], v[50:53]
	v_mfma_f32_16x16x32_bf16 v[46:49], v[146:149], v[178:181], v[46:49]
	v_mfma_f32_16x16x32_bf16 v[34:37], v[138:141], v[186:189], v[34:37]
	v_mfma_f32_16x16x32_bf16 v[30:33], v[146:149], v[186:189], v[30:33]
	v_mfma_f32_16x16x32_bf16 v[18:21], v[138:141], v[216:219], v[18:21]
	v_mfma_f32_16x16x32_bf16 v[14:17], v[146:149], v[216:219], v[14:17]
	s_setprio 0
	s_setprio 1
	v_mfma_f32_16x16x32_bf16 v[58:61], v[150:153], v[166:169], v[58:61]
	v_mfma_f32_16x16x32_bf16 v[54:57], v[158:161], v[166:169], v[54:57]
	v_mfma_f32_16x16x32_bf16 v[42:45], v[150:153], v[174:177], v[42:45]
	v_mfma_f32_16x16x32_bf16 v[38:41], v[158:161], v[174:177], v[38:41]
	v_mfma_f32_16x16x32_bf16 v[26:29], v[150:153], v[182:185], v[26:29]
	v_mfma_f32_16x16x32_bf16 v[22:25], v[158:161], v[182:185], v[22:25]
	v_mfma_f32_16x16x32_bf16 v[10:13], v[150:153], v[212:215], v[10:13]
	v_mfma_f32_16x16x32_bf16 v[4:7], v[158:161], v[212:215], v[6:9]
	v_mfma_f32_16x16x32_bf16 v[58:61], v[154:157], v[170:173], v[58:61]
	v_mfma_f32_16x16x32_bf16 v[54:57], v[162:165], v[170:173], v[54:57]
	v_mfma_f32_16x16x32_bf16 v[42:45], v[154:157], v[178:181], v[42:45]
	v_mfma_f32_16x16x32_bf16 v[38:41], v[162:165], v[178:181], v[38:41]
	v_mfma_f32_16x16x32_bf16 v[26:29], v[154:157], v[186:189], v[26:29]
	v_mfma_f32_16x16x32_bf16 v[22:25], v[162:165], v[186:189], v[22:25]
	v_mfma_f32_16x16x32_bf16 v[10:13], v[154:157], v[216:219], v[10:13]
	v_mfma_f32_16x16x32_bf16 v[4:7], v[162:165], v[216:219], v[4:7]
	s_setprio 0
	s_barrier
	s_add_i32 s2, 0, 0x18000
	v_add_u32_e32 v3, s2, v209
	s_add_i32 s95, 0, 0x1c000
	ds_read_b128 v[134:137], v3
	ds_read_b128 v[138:141], v3 offset:1024
	ds_read_b128 v[142:145], v3 offset:2048
	ds_read_b128 v[146:149], v3 offset:3072
	v_add_u32_e32 v3, s95, v209
	ds_read_b128 v[150:153], v3
	ds_read_b128 v[154:157], v3 offset:1024
	ds_read_b128 v[158:161], v3 offset:2048
	ds_read_b128 v[162:165], v3 offset:3072
	s_add_u32 s64, s64, 0x40000
	s_addc_u32 s65, s65, 0
	s_mov_b32 m0, s67
	v_lshl_add_u64 v[8:9], s[64:65], 0, v[190:191]
	ds_read_b128 v[166:169], v210 offset:32768
	ds_read_b128 v[170:173], v210 offset:33792
	ds_read_b128 v[174:177], v210 offset:34816
	ds_read_b128 v[178:181], v210 offset:35840
	ds_read_b128 v[182:185], v210 offset:36864
	ds_read_b128 v[186:189], v210 offset:37888
	ds_read_b128 v[212:215], v210 offset:38912
	ds_read_b128 v[216:219], v210 offset:39936
	global_load_lds_dwordx4 v[8:9], off
	v_lshl_add_u64 v[8:9], s[64:65], 0, v[194:195]
	s_mov_b32 m0, s68
	s_nop 0
	global_load_lds_dwordx4 v[8:9], off
	s_waitcnt vmcnt(8)
	s_waitcnt lgkmcnt(0)
	s_barrier
	s_setprio 1
	s_waitcnt lgkmcnt(0)
	v_mfma_f32_16x16x32_bf16 v[130:133], v[134:137], v[166:169], v[130:133]
	v_mfma_f32_16x16x32_bf16 v[126:129], v[142:145], v[166:169], v[126:129]
	v_mfma_f32_16x16x32_bf16 v[114:117], v[134:137], v[174:177], v[114:117]
	v_mfma_f32_16x16x32_bf16 v[110:113], v[142:145], v[174:177], v[110:113]
	v_mfma_f32_16x16x32_bf16 v[98:101], v[134:137], v[182:185], v[98:101]
	v_mfma_f32_16x16x32_bf16 v[94:97], v[142:145], v[182:185], v[94:97]
	v_mfma_f32_16x16x32_bf16 v[82:85], v[134:137], v[212:215], v[82:85]
	v_mfma_f32_16x16x32_bf16 v[78:81], v[142:145], v[212:215], v[78:81]
	v_mfma_f32_16x16x32_bf16 v[130:133], v[138:141], v[170:173], v[130:133]
	v_mfma_f32_16x16x32_bf16 v[126:129], v[146:149], v[170:173], v[126:129]
	v_mfma_f32_16x16x32_bf16 v[114:117], v[138:141], v[178:181], v[114:117]
	v_mfma_f32_16x16x32_bf16 v[110:113], v[146:149], v[178:181], v[110:113]
	v_mfma_f32_16x16x32_bf16 v[98:101], v[138:141], v[186:189], v[98:101]
	v_mfma_f32_16x16x32_bf16 v[94:97], v[146:149], v[186:189], v[94:97]
	v_mfma_f32_16x16x32_bf16 v[82:85], v[138:141], v[216:219], v[82:85]
	v_mfma_f32_16x16x32_bf16 v[78:81], v[146:149], v[216:219], v[78:81]
	s_setprio 0
	s_setprio 1
	v_mfma_f32_16x16x32_bf16 v[122:125], v[150:153], v[166:169], v[122:125]
	v_mfma_f32_16x16x32_bf16 v[118:121], v[158:161], v[166:169], v[118:121]
	v_mfma_f32_16x16x32_bf16 v[106:109], v[150:153], v[174:177], v[106:109]
	v_mfma_f32_16x16x32_bf16 v[102:105], v[158:161], v[174:177], v[102:105]
	v_mfma_f32_16x16x32_bf16 v[90:93], v[150:153], v[182:185], v[90:93]
	v_mfma_f32_16x16x32_bf16 v[86:89], v[158:161], v[182:185], v[86:89]
	v_mfma_f32_16x16x32_bf16 v[74:77], v[150:153], v[212:215], v[74:77]
	v_mfma_f32_16x16x32_bf16 v[70:73], v[158:161], v[212:215], v[70:73]
	v_mfma_f32_16x16x32_bf16 v[122:125], v[154:157], v[170:173], v[122:125]
	v_mfma_f32_16x16x32_bf16 v[118:121], v[162:165], v[170:173], v[118:121]
	v_mfma_f32_16x16x32_bf16 v[106:109], v[154:157], v[178:181], v[106:109]
	v_mfma_f32_16x16x32_bf16 v[102:105], v[162:165], v[178:181], v[102:105]
	v_mfma_f32_16x16x32_bf16 v[90:93], v[154:157], v[186:189], v[90:93]
	v_mfma_f32_16x16x32_bf16 v[86:89], v[162:165], v[186:189], v[86:89]
	v_mfma_f32_16x16x32_bf16 v[74:77], v[154:157], v[216:219], v[74:77]
	v_mfma_f32_16x16x32_bf16 v[70:73], v[162:165], v[216:219], v[70:73]
	s_setprio 0
	s_barrier
; #define PG8_STAGE(bufoff, gbase, voff) do { _Pragma("unroll") for (int _i = 0; _i < 2; ++_i) \
;         __builtin_amdgcn_global_load_lds((const unsigned*)((const char*)(gbase) + (voff)[_i]), (PG8_LAS unsigned*)(lds + (bufoff) + ldsw + _i * 8192), 16, 0, 0); } while (0)
; #define PG8_LDA(dst, b, h) do { _Pragma("unroll") for (int m = 0; m < 4; ++m) _Pragma("unroll") for (int k = 0; k < 2; ++k) dst[m][k] = *(const PG8_LAS bf16x8*)(lds + PG8_SA(b, h) + aoff + m * 2048 + k * 1024); } while (0)
; #define PG8_LDB(dst, b, h) do { _Pragma("unroll") for (int n = 0; n < 2; ++n) _Pragma("unroll") for (int k = 0; k < 2; ++k) dst[n][k] = *(const PG8_LAS bf16x8*)(lds + PG8_SB(b, h) + boff + n * 2048 + k * 1024); } while (0)
; #define PG8_MMA(ai, bj, At, Bt) do { __builtin_amdgcn_s_setprio(1); _Pragma("unroll") for (int m = 0; m < 4; ++m) _Pragma("unroll") for (int n = 0; n < 2; ++n) _Pragma("unroll") for (int k = 0; k < 2; ++k) \
;         acc[ai][bj][m][n] = __builtin_amdgcn_mfma_f32_16x16x32_bf16(Bt[n][k], At[m][k], acc[ai][bj][m][n], 0, 0, 0); __builtin_amdgcn_s_setprio(0); } while (0)
; #define PG8_WAIT_V(n) asm volatile("s_waitcnt vmcnt(" #n ")" ::: "memory")
; #define PG8_WAIT_L(n) asm volatile("s_waitcnt lgkmcnt(" #n ")" ::: "memory")
; #define PG8_BAR __builtin_amdgcn_s_barrier()
; #define PG8_SCHED __builtin_amdgcn_sched_barrier(0)
; template <class Epi, class Sched, bool ALIGN_EPI = false, bool SP2 = false>
; __device__ __forceinline__ void gemm_phase(PG8_LAS unsigned char* lds, const Gemm g, const Sched& S, const Epi& E) {
;     ...
;             PG8_LDA(At, 0, 1); PG8_STAGE(PG8_SB(0, 0), b2, voffB); PG8_STAGE(PG8_SB(0, 1), b2 + hstep, voffB); PG8_STAGE(PG8_SA(0, 0), a2, voffA);
;             PG8_WAIT_V(8); PG8_WAIT_L(0); PG8_BAR; PG8_MMA(1, 0, At, B0); PG8_MMA(1, 1, At, B1); PG8_BAR; PG8_SCHED;
;             PG8_LDB(B0, 1, 0); PG8_LDB(B1, 1, 1); PG8_SCHED; PG8_LDA(At, 1, 0); PG8_STAGE(PG8_SA(0, 1), a2 + hstep, voffA);
;             PG8_WAIT_V(8); PG8_WAIT_L(0); PG8_BAR; PG8_MMA(0, 0, At, B0); PG8_MMA(0, 1, At, B1); PG8_BAR; PG8_SCHED;
;             PG8_LDA(At, 1, 1); PG8_STAGE(PG8_SB(1, 0), b3, voffB); PG8_STAGE(PG8_SB(1, 1), b3 + hstep, voffB); PG8_STAGE(PG8_SA(1, 0), a3, voffA);
;             PG8_WAIT_V(8); PG8_WAIT_L(0); PG8_BAR; PG8_MMA(1, 0, At, B0); PG8_MMA(1, 1, At, B1); PG8_BAR; PG8_SCHED;
	s_add_i32 s2, s2, s58
	v_lshl_add_u64 v[8:9], v[220:221], 0, s[22:23]
	s_mov_b32 m0, s2
	ds_read_b128 v[166:169], v210 offset:49152
	ds_read_b128 v[170:173], v210 offset:50176
	ds_read_b128 v[174:177], v210 offset:51200
	ds_read_b128 v[178:181], v210 offset:52224
	ds_read_b128 v[182:185], v210 offset:53248
	ds_read_b128 v[186:189], v210 offset:54272
	ds_read_b128 v[212:215], v210 offset:55296
	ds_read_b128 v[216:219], v210 offset:56320
	global_load_lds_dwordx4 v[8:9], off
	s_add_i32 m0, s2, 0x2000
	s_add_u32 s62, s62, 0x40080
	v_lshl_add_u64 v[8:9], v[222:223], 0, s[22:23]
	s_addc_u32 s63, s63, 0
	s_add_i32 s2, s95, s58
	global_load_lds_dwordx4 v[8:9], off
	v_lshl_add_u64 v[8:9], s[62:63], 0, v[192:193]
	s_mov_b32 m0, s2
	s_nop 0
	global_load_lds_dwordx4 v[8:9], off
	v_lshl_add_u64 v[8:9], s[62:63], 0, v[196:197]
	s_add_i32 m0, s2, 0x2000
	s_nop 0
	global_load_lds_dwordx4 v[8:9], off
	v_lshl_add_u64 v[8:9], v[224:225], 0, s[22:23]
	s_mov_b32 m0, s72
	s_nop 0
	global_load_lds_dwordx4 v[8:9], off
	v_lshl_add_u64 v[8:9], v[226:227], 0, s[22:23]
	s_mov_b32 m0, s73
	s_nop 0
	global_load_lds_dwordx4 v[8:9], off
	s_waitcnt vmcnt(8)
	s_waitcnt lgkmcnt(0)
	s_barrier
	s_setprio 1
	s_waitcnt lgkmcnt(0)
	v_mfma_f32_16x16x32_bf16 v[66:69], v[134:137], v[166:169], v[66:69]
	v_mfma_f32_16x16x32_bf16 v[62:65], v[142:145], v[166:169], v[62:65]
	v_mfma_f32_16x16x32_bf16 v[50:53], v[134:137], v[174:177], v[50:53]
	v_mfma_f32_16x16x32_bf16 v[46:49], v[142:145], v[174:177], v[46:49]
	v_mfma_f32_16x16x32_bf16 v[34:37], v[134:137], v[182:185], v[34:37]
	v_mfma_f32_16x16x32_bf16 v[30:33], v[142:145], v[182:185], v[30:33]
	v_mfma_f32_16x16x32_bf16 v[18:21], v[134:137], v[212:215], v[18:21]
	v_mfma_f32_16x16x32_bf16 v[14:17], v[142:145], v[212:215], v[14:17]
	v_mfma_f32_16x16x32_bf16 v[66:69], v[138:141], v[170:173], v[66:69]
	v_mfma_f32_16x16x32_bf16 v[62:65], v[146:149], v[170:173], v[62:65]
	v_mfma_f32_16x16x32_bf16 v[50:53], v[138:141], v[178:181], v[50:53]
	v_mfma_f32_16x16x32_bf16 v[46:49], v[146:149], v[178:181], v[46:49]
	v_mfma_f32_16x16x32_bf16 v[34:37], v[138:141], v[186:189], v[34:37]
	v_mfma_f32_16x16x32_bf16 v[30:33], v[146:149], v[186:189], v[30:33]
	v_mfma_f32_16x16x32_bf16 v[18:21], v[138:141], v[216:219], v[18:21]
	v_mfma_f32_16x16x32_bf16 v[14:17], v[146:149], v[216:219], v[14:17]
	s_setprio 0
	s_setprio 1
	v_mfma_f32_16x16x32_bf16 v[58:61], v[150:153], v[166:169], v[58:61]
	v_mfma_f32_16x16x32_bf16 v[54:57], v[158:161], v[166:169], v[54:57]
	v_mfma_f32_16x16x32_bf16 v[42:45], v[150:153], v[174:177], v[42:45]
	v_mfma_f32_16x16x32_bf16 v[38:41], v[158:161], v[174:177], v[38:41]
	v_mfma_f32_16x16x32_bf16 v[26:29], v[150:153], v[182:185], v[26:29]
	v_mfma_f32_16x16x32_bf16 v[22:25], v[158:161], v[182:185], v[22:25]
	v_mfma_f32_16x16x32_bf16 v[8:11], v[150:153], v[212:215], v[10:13]
	v_mfma_f32_16x16x32_bf16 v[4:7], v[158:161], v[212:215], v[4:7]
	v_mfma_f32_16x16x32_bf16 v[58:61], v[154:157], v[170:173], v[58:61]
	v_mfma_f32_16x16x32_bf16 v[54:57], v[162:165], v[170:173], v[54:57]
	v_mfma_f32_16x16x32_bf16 v[42:45], v[154:157], v[178:181], v[42:45]
	v_mfma_f32_16x16x32_bf16 v[38:41], v[162:165], v[178:181], v[38:41]
	v_mfma_f32_16x16x32_bf16 v[26:29], v[154:157], v[186:189], v[26:29]
	v_mfma_f32_16x16x32_bf16 v[22:25], v[162:165], v[186:189], v[22:25]
	v_mfma_f32_16x16x32_bf16 v[10:13], v[154:157], v[216:219], v[8:11]
	v_mfma_f32_16x16x32_bf16 v[6:9], v[162:165], v[216:219], v[4:7]
	s_setprio 0
	s_barrier
	s_add_i32 s94, s94, 2
	s_add_u32 s60, s60, 0x100
	s_addc_u32 s61, s61, 0
	s_cmp_gt_u32 s94, 13
	s_cbranch_scc1 .LBB0_590

; #define PG8_STAGE(bufoff, gbase, voff) do { _Pragma("unroll") for (int _i = 0; _i < 2; ++_i) \
;         __builtin_amdgcn_global_load_lds((const unsigned*)((const char*)(gbase) + (voff)[_i]), (PG8_LAS unsigned*)(lds + (bufoff) + ldsw + _i * 8192), 16, 0, 0); } while (0)
; #define PG8_WAIT_V(n) asm volatile("s_waitcnt vmcnt(" #n ")" ::: "memory")
; #define PG8_BAR __builtin_amdgcn_s_barrier()
;     __device__ __forceinline__ void init(f32x4 (&acc)[2][2][4][2], const Unit& u, int wr, int wc, int fr, int fq) const {
;         asm volatile("" : "+v"(fr)); asm volatile("" : "+v"(fq));
; #pragma unroll
;         for (int ai = 0; ai < 2; ++ai)
; #pragma unroll
;             for (int m = 0; m < 4; ++m) { const size_t off = ((size_t)u.pm * 256 + 128 * ai + 64 * wr + 16 * m + fr) * DM + u.pn * 256 + 32 * wc + 4 * fq;
; #pragma unroll
;                 for (int bj = 0; bj < 2; ++bj)
; #pragma unroll
;                     for (int n = 0; n < 2; ++n) acc[ai][bj][m][n] = __builtin_nontemporal_load((const f32x4*)(x + off + bj * HALF + n * 16)); }
;     }
; template <class Epi, class Sched, bool ALIGN_EPI = false, bool SP2 = false>
; __device__ __forceinline__ void gemm_phase(PG8_LAS unsigned char* lds, const Gemm g, const Sched& S, const Epi& E) {
;     ...
;     if constexpr (Epi::HAS_INIT) E.init(acc, cur, wr, wc, fr, fq);
;     bf16x8 At[4][2], B0[2][2], B1[2][2];
;     const char* cA = (const char*)g.A + (size_t)cur.pm * tstep; const char* cB = (const char*)g.Bt + (size_t)cur.pn * tstep;
;     S.a_ready(cur);
;     if constexpr (SP2) {
;         PG8_STAGE(PG8_SB(0, 0), cB, voffB); PG8_STAGE(PG8_SB(0, 1), cB + hstep, voffB); PG8_STAGE(PG8_SA(0, 0), cA, voffA); PG8_STAGE(PG8_SA(0, 1), cA + hstep, voffA);
;         if (wr == 1) PG8_BAR;
;         PG8_WAIT_V(2); PG8_BAR;
;         PG8_STAGE(PG8_SB(1, 0), cB + kstep, voffB); PG8_STAGE(PG8_SA(1, 0), cA + kstep, voffA); PG8_STAGE(PG8_SB(1, 1), cB + hstep + kstep, voffB);
;         PG8_WAIT_V(6); PG8_BAR;
;     } else {
;         PG8_STAGE(PG8_SB(0, 0), cB, voffB); PG8_STAGE(PG8_SA(0, 0), cA, voffA); PG8_STAGE(PG8_SB(0, 1), cB + hstep, voffB); PG8_STAGE(PG8_SA(0, 1), cA + hstep, voffA);
;         if (wr == 1) PG8_BAR;
;         PG8_WAIT_V(4); PG8_BAR;
;         PG8_STAGE(PG8_SB(1, 0), cB + kstep, voffB); PG8_STAGE(PG8_SA(1, 0), cA + kstep, voffA); PG8_STAGE(PG8_SB(1, 1), cB + hstep + kstep, voffB);
.LBB0_704:
.LBB0_705:
	s_xor_b64 s[36:37], s[4:5], -1
	s_add_u32 s33, s14, 0x1200000
	v_lshlrev_b32_e32 v2, 4, v0
	s_addc_u32 s54, s15, 0
	v_and_b32_e32 v3, 32, v0
	s_waitcnt vmcnt(0)
	v_or_b32_e32 v146, 0x2000, v2
	s_add_u32 s55, s14, 0x1000000
	v_bfe_u32 v1, v0, 2, 4
	v_bitop3_b32 v144, v2, v3, 48 bitop3:0x6c
	v_and_b32_e32 v145, 64, v0
	v_lshrrev_b32_e32 v2, 7, v146
	s_movk_i32 s2, 0x70
	s_addc_u32 s56, s15, 0
	v_or_b32_e32 v3, v144, v145
	v_lshrrev_b32_e32 v4, 3, v0
	v_and_or_b32 v2, v2, s2, v1
	v_and_b32_e32 v142, 15, v0
	s_lshl_b32 s2, s34, 4
	s_lshr_b32 s26, s34, 8
	v_and_or_b32 v4, v4, 48, v1
	v_lshl_or_b32 v132, v2, 11, v3
	s_and_b32 s57, s2, 0xfffffc00
	s_lshr_b32 s2, s34, 1
	v_mov_b32_e32 v2, v142
	s_mov_b32 s7, 0
	s_ashr_i32 s31, s30, 31
	s_lshl_b32 s8, s28, 8
	v_lshl_or_b32 v130, v4, 11, v3
	s_lshl_b32 s4, s26, 6
	s_and_b32 s27, s2, 0x60
	s_mov_b32 s5, s7
	v_ashrrev_i32_e32 v3, 31, v2
	s_ashr_i32 s9, s8, 31
	s_lshl_b64 s[10:11], s[30:31], 20
	v_bfe_u32 v143, v0, 4, 2
	v_lshl_add_u64 v[2:3], v[2:3], 0, s[4:5]
	s_add_u32 s10, s16, s10
	v_mov_b32_e32 v4, v143
	v_lshlrev_b64 v[2:3], 12, v[2:3]
	s_addc_u32 s11, s17, s11
	s_lshl_b64 s[84:85], s[8:9], 2
	s_add_u32 s84, s84, s10
	s_addc_u32 s85, s85, s11
	v_lshl_add_u64 v[2:3], s[10:11], 0, v[2:3]
	v_lshlrev_b32_e32 v4, 2, v4
	v_lshl_add_u64 v[2:3], s[8:9], 2, v[2:3]
	s_lshl_b32 s6, s27, 2
	v_ashrrev_i32_e32 v5, 31, v4
	v_lshl_add_u64 v[2:3], v[2:3], 0, s[6:7]
	v_lshl_add_u64 v[114:115], v[4:5], 2, v[2:3]
	v_add_u32_e32 v234, s4, v142
	v_lshlrev_b32_e32 v234, 12, v234
	v_lshl_add_u32 v234, v143, 4, v234
	v_add_u32_e32 v234, s6, v234
	v_mov_b32_e32 v235, 0
	s_mov_b32 s58, 0x10000
	v_add_co_u32_e32 v36, vcc, s58, v114
	s_mov_b32 s59, 0x20000
	s_nop 0
	v_addc_co_u32_e32 v37, vcc, 0, v115, vcc
	v_add_co_u32_e32 v52, vcc, s59, v114
	s_mov_b32 s60, 0x30000
	s_nop 0
	v_addc_co_u32_e32 v53, vcc, 0, v115, vcc
	v_add_co_u32_e32 v68, vcc, s60, v114
	s_mov_b32 s61, 0x80000
	s_nop 0
	v_addc_co_u32_e32 v69, vcc, 0, v115, vcc
	v_add_co_u32_e32 v84, vcc, s61, v114
	s_mov_b32 s62, 0x90000
	s_nop 0
	v_addc_co_u32_e32 v85, vcc, 0, v115, vcc
	v_add_co_u32_e32 v100, vcc, s62, v114
	s_mov_b32 s63, 0xa0000
	s_nop 0
	v_addc_co_u32_e32 v101, vcc, 0, v115, vcc
	s_ashr_i32 s29, s28, 31
	s_mov_b64 s[8:9], 0x10000
	s_mov_b64 s[10:11], 0x20000
	s_mov_b64 s[12:13], 0x30000
	s_mov_b64 s[14:15], 0x80000
	s_mov_b64 s[18:19], 0x90000
	s_mov_b64 s[20:21], 0xa0000
	v_add_co_u32_e32 v118, vcc, s63, v114
	s_lshl_b64 s[24:25], s[30:31], 19
	s_lshl_b64 s[40:41], s[28:29], 19
	v_lshl_add_u64 v[34:35], v[114:115], 0, s[8:9]
	v_lshl_add_u64 v[50:51], v[114:115], 0, s[10:11]
	v_lshl_add_u64 v[66:67], v[114:115], 0, s[12:13]
	v_lshl_add_u64 v[82:83], v[114:115], 0, s[14:15]
	v_lshl_add_u64 v[98:99], v[114:115], 0, s[18:19]
	v_lshl_add_u64 v[116:117], v[114:115], 0, s[20:21]
	v_addc_co_u32_e32 v119, vcc, 0, v115, vcc
	s_mov_b32 s2, 0xb0000
	s_add_u32 s46, s55, s40
	s_mov_b64 s[22:23], 0xb0000
	v_add_co_u32_e32 v118, vcc, s2, v114
	s_addc_u32 s47, s56, s41
	s_add_i32 s64, s57, 0
	v_lshl_add_u64 v[126:127], v[114:115], 0, s[22:23]
	v_addc_co_u32_e32 v119, vcc, 0, v115, vcc
	s_add_i32 m0, s64, 0x10000
	v_mov_b64_e32 v[2:3], 0
	v_mov_b64_e32 v[4:5], 0
	v_mov_b64_e32 v[6:7], 0
	v_mov_b64_e32 v[8:9], 0
	v_mov_b64_e32 v[10:11], 0
	v_mov_b64_e32 v[12:13], 0
	v_mov_b64_e32 v[14:15], 0
	v_mov_b64_e32 v[16:17], 0
	v_mov_b64_e32 v[18:19], 0
	v_mov_b64_e32 v[20:21], 0
	v_mov_b64_e32 v[22:23], 0
	v_mov_b64_e32 v[24:25], 0
	v_mov_b64_e32 v[26:27], 0
	v_mov_b64_e32 v[28:29], 0
	v_mov_b64_e32 v[30:31], 0
	v_mov_b64_e32 v[32:33], 0
	v_mov_b64_e32 v[34:35], 0
	v_mov_b64_e32 v[36:37], 0
	v_mov_b64_e32 v[38:39], 0
	v_mov_b64_e32 v[40:41], 0
	v_mov_b64_e32 v[42:43], 0
	v_mov_b64_e32 v[44:45], 0
	v_mov_b64_e32 v[46:47], 0
	v_mov_b64_e32 v[48:49], 0
	v_mov_b64_e32 v[50:51], 0
	v_mov_b64_e32 v[52:53], 0
	v_mov_b64_e32 v[54:55], 0
	v_mov_b64_e32 v[56:57], 0
	v_mov_b64_e32 v[58:59], 0
	v_mov_b64_e32 v[60:61], 0
	v_mov_b64_e32 v[62:63], 0
	v_mov_b64_e32 v[64:65], 0
	v_mov_b64_e32 v[66:67], 0
	v_mov_b64_e32 v[68:69], 0
	v_mov_b64_e32 v[70:71], 0
	v_mov_b64_e32 v[72:73], 0
	v_mov_b64_e32 v[74:75], 0
	v_mov_b64_e32 v[76:77], 0
	v_mov_b64_e32 v[78:79], 0
	v_mov_b64_e32 v[80:81], 0
	v_mov_b64_e32 v[82:83], 0
	v_mov_b64_e32 v[84:85], 0
	v_mov_b64_e32 v[86:87], 0
	v_mov_b64_e32 v[88:89], 0
	v_mov_b64_e32 v[90:91], 0
	v_mov_b64_e32 v[92:93], 0
	v_mov_b64_e32 v[94:95], 0
	v_mov_b64_e32 v[96:97], 0
	v_mov_b64_e32 v[98:99], 0
	v_mov_b64_e32 v[100:101], 0
	v_mov_b64_e32 v[102:103], 0
	v_mov_b64_e32 v[104:105], 0
	v_mov_b64_e32 v[106:107], 0
	v_mov_b64_e32 v[108:109], 0
	v_mov_b64_e32 v[110:111], 0
	v_mov_b64_e32 v[112:113], 0
	v_mov_b64_e32 v[114:115], 0
	v_mov_b64_e32 v[116:117], 0
	v_mov_b64_e32 v[118:119], 0
	v_mov_b64_e32 v[120:121], 0
	v_mov_b64_e32 v[122:123], 0
	v_mov_b64_e32 v[124:125], 0
	v_mov_b64_e32 v[126:127], 0
	v_mov_b64_e32 v[128:129], 0
	v_mov_b32_e32 v131, 0
	global_load_lds_dwordx4 v130, s[46:47]
	s_add_i32 m0, s64, 0x12000
	s_add_u32 s40, s46, 0x40000
	global_load_lds_dwordx4 v132, s[46:47]
	s_addc_u32 s41, s47, 0
	s_add_i32 m0, s64, 0x14000
	v_mov_b32_e32 v133, v131
	global_load_lds_dwordx4 v130, s[40:41]
	s_add_i32 m0, s64, 0x16000
	s_add_u32 s48, s33, s24
	s_addc_u32 s49, s54, s25
	s_add_i32 s65, s64, 0x2000
	global_load_lds_dwordx4 v132, s[40:41]
	s_mov_b32 m0, s64
	s_add_u32 s24, s48, 0x40000
	global_load_lds_dwordx4 v130, s[48:49]
	s_mov_b32 m0, s65
	s_addc_u32 s25, s49, 0
	s_add_i32 s66, s64, 0x4000
	global_load_lds_dwordx4 v132, s[48:49]
	s_mov_b32 m0, s66
	s_add_i32 s67, s64, 0x6000
	global_load_lds_dwordx4 v130, s[24:25]
	s_mov_b32 m0, s67
	s_cmp_eq_u32 s26, 1
	global_load_lds_dwordx4 v132, s[24:25]
	v_lshl_add_u64 v[140:141], s[46:47], 0, v[130:131]
	v_lshl_add_u64 v[138:139], s[46:47], 0, v[132:133]
	v_lshl_add_u64 v[134:135], s[48:49], 0, v[130:131]
	s_cselect_b64 s[24:25], -1, 0
	s_cmp_lg_u32 s26, 1
	v_lshl_add_u64 v[136:137], s[48:49], 0, v[132:133]
	s_cbranch_scc1 .LBB0_707
	s_barrier
; #define PG8_STAGE(bufoff, gbase, voff) do { _Pragma("unroll") for (int _i = 0; _i < 2; ++_i) \
;         __builtin_amdgcn_global_load_lds((const unsigned*)((const char*)(gbase) + (voff)[_i]), (PG8_LAS unsigned*)(lds + (bufoff) + ldsw + _i * 8192), 16, 0, 0); } while (0)
; #define PG8_WAIT_V(n) asm volatile("s_waitcnt vmcnt(" #n ")" ::: "memory")
; #define PG8_BAR __builtin_amdgcn_s_barrier()
;     __device__ __forceinline__ void init(f32x4 (&acc)[2][2][4][2], const Unit& u, int wr, int wc, int fr, int fq) const {
;         asm volatile("" : "+v"(fr)); asm volatile("" : "+v"(fq));
; #pragma unroll
;         for (int ai = 0; ai < 2; ++ai)
; #pragma unroll
;             for (int m = 0; m < 4; ++m) { const size_t off = ((size_t)u.pm * 256 + 128 * ai + 64 * wr + 16 * m + fr) * DM + u.pn * 256 + 32 * wc + 4 * fq;
; #pragma unroll
;                 for (int bj = 0; bj < 2; ++bj)
; #pragma unroll
;                     for (int n = 0; n < 2; ++n) acc[ai][bj][m][n] = __builtin_nontemporal_load((const f32x4*)(x + off + bj * HALF + n * 16)); }
;     }
; template <class Epi, class Sched, bool ALIGN_EPI = false, bool SP2 = false>
; __device__ __forceinline__ void gemm_phase(PG8_LAS unsigned char* lds, const Gemm g, const Sched& S, const Epi& E) {
;     ...
;         PG8_STAGE(PG8_SB(1, 0), cB + kstep, voffB); PG8_STAGE(PG8_SA(1, 0), cA + kstep, voffA); PG8_STAGE(PG8_SB(1, 1), cB + hstep + kstep, voffB);
;         PG8_WAIT_V(6); PG8_BAR;
;     } else {
;         PG8_STAGE(PG8_SB(0, 0), cB, voffB); PG8_STAGE(PG8_SA(0, 0), cA, voffA); PG8_STAGE(PG8_SB(0, 1), cB + hstep, voffB); PG8_STAGE(PG8_SA(0, 1), cA + hstep, voffA);
;         if (wr == 1) PG8_BAR;
;         PG8_WAIT_V(4); PG8_BAR;
;         PG8_STAGE(PG8_SB(1, 0), cB + kstep, voffB); PG8_STAGE(PG8_SA(1, 0), cA + kstep, voffA); PG8_STAGE(PG8_SB(1, 1), cB + hstep + kstep, voffB);
;         PG8_WAIT_V(6); PG8_BAR;
.LBB0_707:
	s_lshl_b32 s2, s26, 13
	s_lshl_b32 s29, s27, 7
	s_mov_b64 s[26:27], 0x80
	s_add_i32 m0, s64, 0x18000
	v_lshl_add_u64 v[140:141], v[140:141], 0, s[26:27]
	s_waitcnt vmcnt(2)
	s_barrier
	global_load_lds_dwordx4 v[140:141], off
	v_lshl_add_u64 v[138:139], v[138:139], 0, s[26:27]
	s_add_i32 m0, s64, 0x1a000
	s_add_i32 s68, s64, 0x8000
	s_add_i32 s69, s64, 0xa000
	global_load_lds_dwordx4 v[138:139], off
	v_lshl_add_u64 v[134:135], v[134:135], 0, s[26:27]
	s_mov_b32 m0, s68
	s_add_u32 s40, s46, 0x40080
	global_load_lds_dwordx4 v[134:135], off
	v_lshl_add_u64 v[134:135], v[136:137], 0, s[26:27]
	s_mov_b32 m0, s69
	s_addc_u32 s41, s47, 0
	global_load_lds_dwordx4 v[134:135], off
	s_add_i32 m0, s64, 0x1c000
	v_lshl_add_u64 v[134:135], s[40:41], 0, v[130:131]
	global_load_lds_dwordx4 v[134:135], off
	v_lshl_add_u64 v[134:135], s[40:41], 0, v[132:133]
	s_add_i32 m0, s64, 0x1e000
	s_movk_i32 s31, 0x3c0
	global_load_lds_dwordx4 v[134:135], off
	v_lshl_add_u64 v[232:233], v[234:235], 0, s[84:85]
	global_load_dwordx4 v[216:219], v[232:233], off nt
	global_load_dwordx4 v[220:223], v[232:233], off offset:64 nt
	global_load_dwordx4 v[224:227], v[232:233], off offset:512 nt
	global_load_dwordx4 v[228:231], v[232:233], off offset:576 nt
	v_or_b32_e32 v134, s4, v142
	v_lshlrev_b32_e32 v135, 4, v143
	v_lshlrev_b32_e32 v136, 6, v134
	v_lshlrev_b32_e32 v134, 2, v134
	v_and_or_b32 v136, v136, s31, v135
	v_and_b32_e32 v134, 32, v134
	v_bitop3_b32 v136, v136, s2, v134 bitop3:0xde
	v_lshlrev_b32_e32 v134, 6, v0
	v_and_or_b32 v134, v134, s31, v135
	v_lshlrev_b32_e32 v135, 2, v0
	s_cmpk_lt_u32 s34, 0x100
	v_and_b32_e32 v135, 32, v135
	s_cselect_b64 s[34:35], -1, 0
	s_add_i32 s2, s38, 32
	v_bitop3_b32 v138, s29, v134, v135 bitop3:0xf6
	s_lshl_b32 s29, s72, 4
	s_ashr_i32 s2, s2, 2
	s_and_b32 s39, s38, 7
	s_add_i32 s2, s2, s29
	s_or_b32 s29, s39, s29
	v_lshlrev_b32_e32 v0, 8, v0
	v_lshlrev_b32_e32 v135, 4, v146
	s_waitcnt vmcnt(10)
	s_ashr_i32 s70, s3, 31
	s_ashr_i32 s71, s98, 31
	s_and_b32 s31, s38, 3
	s_xor_b32 s29, s29, 15
	s_ashr_i32 s38, s38, 3
	v_and_b32_e32 v0, 0x18000, v0
	v_lshlrev_b32_e32 v134, 11, v1
	v_and_b32_e32 v135, 0x38000, v135
	s_and_b64 s[0:1], s[0:1], exec
	v_or3_b32 v0, v144, v0, v134
	v_or3_b32 v134, v144, v135, v134
	v_cndmask_b32_e64 v137, 0, 1, s[36:37]
	s_cselect_b32 s72, s38, s31
	s_cselect_b32 s73, s29, s2
	v_add_u32_e32 v0, v0, v145
	v_mov_b32_e32 v1, v131
	v_add_u32_e32 v134, v134, v145
	v_mov_b32_e32 v135, v131
	v_cmp_ne_u32_e64 s[0:1], 1, v137
	s_add_i32 s74, 0, 0x10000
	s_add_i32 s75, 0, 0x14000
	v_add_u32_e32 v139, 0, v136
	v_mov_b64_e32 v[136:137], 0x1ff
	s_mov_b32 s29, s7
	s_barrier
	s_branch .LBB0_710

; #define PG8_BAR __builtin_amdgcn_s_barrier()
; template <class Epi, class Sched, bool ALIGN_EPI = false, bool SP2 = false>
; __device__ __forceinline__ void gemm_phase(PG8_LAS unsigned char* lds, const Gemm g, const Sched& S, const Epi& E) {
;     ...
;         if (!has_next) break;
; #pragma unroll
;         for (int a = 0; a < 2; ++a)
; #pragma unroll
;             for (int b = 0; b < 2; ++b)
; #pragma unroll
;                 for (int m = 0; m < 4; ++m)
; #pragma unroll
;                     for (int n = 0; n < 2; ++n) acc[a][b][m][n] = (f32x4){0.f, 0.f, 0.f, 0.f};
;         if constexpr (Epi::HAS_INIT) E.init(acc, nxt, wr, wc, fr, fq);
;         cur = nxt; cA = nA; cB = nB; ++ui;
;         if constexpr (ALIGN_EPI) { if (wr == 1) PG8_BAR; }
;     }
.LBB0_709:
	s_andn2_b64 vcc, exec, s[28:29]
	s_mov_b64 s[84:85], s[86:87]
	s_mov_b32 s28, s38
	s_mov_b32 s30, s36
	s_mov_b64 s[46:47], s[42:43]
	s_mov_b64 s[48:49], s[40:41]
	s_mov_b32 s29, s76
	s_cbranch_vccz .LBB0_728

; #define PG8_STAGE(bufoff, gbase, voff) do { _Pragma("unroll") for (int _i = 0; _i < 2; ++_i) \
;         __builtin_amdgcn_global_load_lds((const unsigned*)((const char*)(gbase) + (voff)[_i]), (PG8_LAS unsigned*)(lds + (bufoff) + ldsw + _i * 8192), 16, 0, 0); } while (0)
; #define PG8_LDA(dst, b, h) do { _Pragma("unroll") for (int m = 0; m < 4; ++m) _Pragma("unroll") for (int k = 0; k < 2; ++k) dst[m][k] = *(const PG8_LAS bf16x8*)(lds + PG8_SA(b, h) + aoff + m * 2048 + k * 1024); } while (0)
; #define PG8_LDB(dst, b, h) do { _Pragma("unroll") for (int n = 0; n < 2; ++n) _Pragma("unroll") for (int k = 0; k < 2; ++k) dst[n][k] = *(const PG8_LAS bf16x8*)(lds + PG8_SB(b, h) + boff + n * 2048 + k * 1024); } while (0)
; #define PG8_MMA(ai, bj, At, Bt) do { __builtin_amdgcn_s_setprio(1); _Pragma("unroll") for (int m = 0; m < 4; ++m) _Pragma("unroll") for (int n = 0; n < 2; ++n) _Pragma("unroll") for (int k = 0; k < 2; ++k) \
;         acc[ai][bj][m][n] = __builtin_amdgcn_mfma_f32_16x16x32_bf16(Bt[n][k], At[m][k], acc[ai][bj][m][n], 0, 0, 0); __builtin_amdgcn_s_setprio(0); } while (0)
; #define PG8_WAIT_V(n) asm volatile("s_waitcnt vmcnt(" #n ")" ::: "memory")
; template <class Epi, class Sched, bool ALIGN_EPI = false, bool SP2 = false>
; __device__ __forceinline__ void gemm_phase(PG8_LAS unsigned char* lds, const Gemm g, const Sched& S, const Epi& E) {
;     ...
;         const bool has_next = S.next(ui + 1, nxt);
;         const char* nA = has_next ? (const char*)g.A + (size_t)nxt.pm * tstep : cA; const char* nB = has_next ? (const char*)g.Bt + (size_t)nxt.pn * tstep : cB;
;         for (int t = 0; t < nt; t += 2) {
;             if constexpr (Epi::HAS_MID) { if (t == nt / 2) E.mid(acc, cur, wr, wc, fr, fq); }
;             const bool last = (t == nt - 2);
;             const char* a1 = cA + (size_t)(t + 1) * kstep;
;             const char* a2 = last ? nA : cA + (size_t)(t + 2) * kstep; const char* b2 = last ? nB : cB + (size_t)(t + 2) * kstep;
;             const char* a3 = a2 + kstep; const char* b3 = b2 + kstep;
;             if (last && has_next) S.a_ready(nxt);
;             if constexpr (SP2) {
;             PG8_LDB(B0, 0, 0); PG8_LDB(B1, 0, 1); PG8_SCHED; PG8_LDA(At, 0, 0); PG8_STAGE(PG8_SA(1, 1), a1 + hstep, voffA);
;             PG8_WAIT_V(8); PG8_WAIT_L(0); PG8_BAR; PG8_MMA(0, 0, At, B0); PG8_MMA(0, 1, At, B1); PG8_BAR; PG8_SCHED;
.LBB0_721:
	s_mov_b32 s36, s31
	s_mov_b32 s38, s37
	s_ashr_i32 s37, s31, 31
	s_lshl_b64 s[40:41], s[36:37], 19
	s_add_u32 s40, s33, s40
	s_addc_u32 s41, s54, s41
	s_and_b64 s[42:43], s[44:45], exec
	s_cselect_b32 s29, s41, s49
	s_cselect_b32 s31, s40, s48
	s_ashr_i32 s39, s38, 31
	s_lshl_b64 s[42:43], s[38:39], 19
	s_add_u32 s42, s55, s42
	s_addc_u32 s43, s56, s43
	s_and_b64 s[52:53], s[44:45], exec
	s_cselect_b32 s39, s43, s47
	s_cselect_b32 s77, s42, s46
	s_add_u32 s48, s48, 0x40080
	s_addc_u32 s49, s49, 0
	s_add_u32 s78, s46, 0x100
	s_addc_u32 s79, s47, 0
	s_mov_b32 s80, -2
	s_lshl_b64 s[86:87], s[36:37], 20
	s_add_u32 s86, s86, s16
	s_addc_u32 s87, s87, s17
	s_lshl_b32 s88, s38, 10
	s_add_u32 s86, s86, s88
	s_addc_u32 s87, s87, 0
.LBB0_722:
	v_add_u32_e32 v140, s74, v138
	ds_read_b128 v[144:147], v140
	ds_read_b128 v[148:151], v140 offset:1024
	ds_read_b128 v[152:155], v140 offset:2048
	ds_read_b128 v[156:159], v140 offset:3072
	v_add_u32_e32 v140, s75, v138
	ds_read_b128 v[160:163], v140
	ds_read_b128 v[164:167], v140 offset:1024
	ds_read_b128 v[168:171], v140 offset:2048
	ds_read_b128 v[172:175], v140 offset:3072
	s_add_u32 s2, s48, 0xfffc0080
	s_addc_u32 s46, s49, -1
	s_cmp_eq_u32 s80, 12
	s_cselect_b32 s53, s29, s46
	s_cselect_b32 s52, s31, s2
	s_cselect_b32 s47, s39, s79
	s_cselect_b32 s46, s77, s78
	v_lshl_add_u64 v[140:141], s[48:49], 0, v[0:1]
	s_add_i32 m0, s64, 0xc000
	ds_read_b128 v[176:179], v139
	ds_read_b128 v[180:183], v139 offset:1024
	ds_read_b128 v[184:187], v139 offset:2048
	ds_read_b128 v[188:191], v139 offset:3072
	ds_read_b128 v[192:195], v139 offset:4096
	ds_read_b128 v[196:199], v139 offset:5120
	ds_read_b128 v[200:203], v139 offset:6144
	ds_read_b128 v[204:207], v139 offset:7168
	global_load_lds_dwordx4 v[140:141], off
	v_lshl_add_u64 v[140:141], s[48:49], 0, v[134:135]
	s_add_i32 m0, s64, 0xe000
	s_nop 0
	global_load_lds_dwordx4 v[140:141], off
	s_waitcnt vmcnt(12)
	s_waitcnt lgkmcnt(0)
	s_barrier
	s_setprio 1
	s_waitcnt lgkmcnt(0)
	v_mfma_f32_16x16x32_bf16 v[2:5], v[144:147], v[176:179], v[2:5]
	v_mfma_f32_16x16x32_bf16 v[6:9], v[152:155], v[176:179], v[6:9]
	v_mfma_f32_16x16x32_bf16 v[22:25], v[144:147], v[184:187], v[22:25]
	v_mfma_f32_16x16x32_bf16 v[18:21], v[152:155], v[184:187], v[18:21]
	v_mfma_f32_16x16x32_bf16 v[38:41], v[144:147], v[192:195], v[38:41]
	v_mfma_f32_16x16x32_bf16 v[34:37], v[152:155], v[192:195], v[34:37]
	v_mfma_f32_16x16x32_bf16 v[54:57], v[144:147], v[200:203], v[54:57]
	v_mfma_f32_16x16x32_bf16 v[50:53], v[152:155], v[200:203], v[50:53]
	v_mfma_f32_16x16x32_bf16 v[2:5], v[148:151], v[180:183], v[2:5]
	v_mfma_f32_16x16x32_bf16 v[6:9], v[156:159], v[180:183], v[6:9]
	v_mfma_f32_16x16x32_bf16 v[22:25], v[148:151], v[188:191], v[22:25]
	v_mfma_f32_16x16x32_bf16 v[18:21], v[156:159], v[188:191], v[18:21]
	v_mfma_f32_16x16x32_bf16 v[38:41], v[148:151], v[196:199], v[38:41]
	v_mfma_f32_16x16x32_bf16 v[34:37], v[156:159], v[196:199], v[34:37]
	v_mfma_f32_16x16x32_bf16 v[54:57], v[148:151], v[204:207], v[54:57]
	v_mfma_f32_16x16x32_bf16 v[50:53], v[156:159], v[204:207], v[50:53]
	s_setprio 0
	s_setprio 1
	v_mfma_f32_16x16x32_bf16 v[10:13], v[160:163], v[176:179], v[10:13]
	v_mfma_f32_16x16x32_bf16 v[14:17], v[168:171], v[176:179], v[14:17]
	v_mfma_f32_16x16x32_bf16 v[26:29], v[160:163], v[184:187], v[26:29]
	v_mfma_f32_16x16x32_bf16 v[30:33], v[168:171], v[184:187], v[30:33]
	v_mfma_f32_16x16x32_bf16 v[42:45], v[160:163], v[192:195], v[42:45]
	v_mfma_f32_16x16x32_bf16 v[46:49], v[168:171], v[192:195], v[46:49]
	v_mfma_f32_16x16x32_bf16 v[58:61], v[160:163], v[200:203], v[58:61]
	v_mfma_f32_16x16x32_bf16 v[62:65], v[168:171], v[200:203], v[62:65]
	v_mfma_f32_16x16x32_bf16 v[10:13], v[164:167], v[180:183], v[10:13]
	v_mfma_f32_16x16x32_bf16 v[14:17], v[172:175], v[180:183], v[14:17]
	v_mfma_f32_16x16x32_bf16 v[26:29], v[164:167], v[188:191], v[26:29]
	v_mfma_f32_16x16x32_bf16 v[30:33], v[172:175], v[188:191], v[30:33]
	v_mfma_f32_16x16x32_bf16 v[42:45], v[164:167], v[196:199], v[42:45]
	v_mfma_f32_16x16x32_bf16 v[46:49], v[172:175], v[196:199], v[46:49]
	v_mfma_f32_16x16x32_bf16 v[58:61], v[164:167], v[204:207], v[58:61]
	v_mfma_f32_16x16x32_bf16 v[62:65], v[172:175], v[204:207], v[62:65]
	s_setprio 0
	s_barrier
	s_add_i32 s2, s74, s57
	v_lshl_add_u64 v[140:141], s[46:47], 0, v[130:131]
	s_mov_b32 m0, s2
	ds_read_b128 v[176:179], v139 offset:16384
	ds_read_b128 v[180:183], v139 offset:17408
	ds_read_b128 v[184:187], v139 offset:18432
	ds_read_b128 v[188:191], v139 offset:19456
	ds_read_b128 v[192:195], v139 offset:20480
	ds_read_b128 v[196:199], v139 offset:21504
	ds_read_b128 v[200:203], v139 offset:22528
	ds_read_b128 v[204:207], v139 offset:23552
	global_load_lds_dwordx4 v[140:141], off
	s_add_i32 m0, s2, 0x2000
	s_add_u32 s82, s46, 0x40000
	v_lshl_add_u64 v[208:209], s[46:47], 0, v[132:133]
	s_addc_u32 s83, s47, 0
	s_add_i32 s2, s75, s57
	global_load_lds_dwordx4 v[208:209], off
	v_lshl_add_u64 v[210:211], s[82:83], 0, v[130:131]
	s_mov_b32 m0, s2
	v_lshl_add_u64 v[212:213], s[52:53], 0, v[132:133]
	global_load_lds_dwordx4 v[210:211], off
	v_lshl_add_u64 v[210:211], s[82:83], 0, v[132:133]
	s_add_i32 m0, s2, 0x2000
	s_nop 0
	global_load_lds_dwordx4 v[210:211], off
	v_lshl_add_u64 v[210:211], s[52:53], 0, v[130:131]
	s_mov_b32 m0, s64
	s_nop 0
	global_load_lds_dwordx4 v[210:211], off
	s_mov_b32 m0, s65
	s_nop 0
	global_load_lds_dwordx4 v[212:213], off
	s_waitcnt vmcnt(12)
	s_waitcnt lgkmcnt(0)
	s_barrier
; #define PG8_STAGE(bufoff, gbase, voff) do { _Pragma("unroll") for (int _i = 0; _i < 2; ++_i) \
;         __builtin_amdgcn_global_load_lds((const unsigned*)((const char*)(gbase) + (voff)[_i]), (PG8_LAS unsigned*)(lds + (bufoff) + ldsw + _i * 8192), 16, 0, 0); } while (0)
; #define PG8_LDA(dst, b, h) do { _Pragma("unroll") for (int m = 0; m < 4; ++m) _Pragma("unroll") for (int k = 0; k < 2; ++k) dst[m][k] = *(const PG8_LAS bf16x8*)(lds + PG8_SA(b, h) + aoff + m * 2048 + k * 1024); } while (0)
; #define PG8_LDB(dst, b, h) do { _Pragma("unroll") for (int n = 0; n < 2; ++n) _Pragma("unroll") for (int k = 0; k < 2; ++k) dst[n][k] = *(const PG8_LAS bf16x8*)(lds + PG8_SB(b, h) + boff + n * 2048 + k * 1024); } while (0)
; #define PG8_MMA(ai, bj, At, Bt) do { __builtin_amdgcn_s_setprio(1); _Pragma("unroll") for (int m = 0; m < 4; ++m) _Pragma("unroll") for (int n = 0; n < 2; ++n) _Pragma("unroll") for (int k = 0; k < 2; ++k) \
;         acc[ai][bj][m][n] = __builtin_amdgcn_mfma_f32_16x16x32_bf16(Bt[n][k], At[m][k], acc[ai][bj][m][n], 0, 0, 0); __builtin_amdgcn_s_setprio(0); } while (0)
; #define PG8_WAIT_V(n) asm volatile("s_waitcnt vmcnt(" #n ")" ::: "memory")
; #define PG8_WAIT_L(n) asm volatile("s_waitcnt lgkmcnt(" #n ")" ::: "memory")
; #define PG8_BAR __builtin_amdgcn_s_barrier()
; #define PG8_SCHED __builtin_amdgcn_sched_barrier(0)
; template <class Epi, class Sched, bool ALIGN_EPI = false, bool SP2 = false>
; __device__ __forceinline__ void gemm_phase(PG8_LAS unsigned char* lds, const Gemm g, const Sched& S, const Epi& E) {
;     ...
;             PG8_LDA(At, 0, 1); PG8_STAGE(PG8_SB(0, 0), b2, voffB); PG8_STAGE(PG8_SB(0, 1), b2 + hstep, voffB); PG8_STAGE(PG8_SA(0, 0), a2, voffA);
;             PG8_WAIT_V(8); PG8_WAIT_L(0); PG8_BAR; PG8_MMA(1, 0, At, B0); PG8_MMA(1, 1, At, B1); PG8_BAR; PG8_SCHED;
;             PG8_LDB(B0, 1, 0); PG8_LDB(B1, 1, 1); PG8_SCHED; PG8_LDA(At, 1, 0); PG8_STAGE(PG8_SA(0, 1), a2 + hstep, voffA);
;             PG8_WAIT_V(8); PG8_WAIT_L(0); PG8_BAR; PG8_MMA(0, 0, At, B0); PG8_MMA(0, 1, At, B1); PG8_BAR; PG8_SCHED;
	s_setprio 1
	s_waitcnt lgkmcnt(0)
	v_mfma_f32_16x16x32_bf16 v[70:73], v[144:147], v[176:179], v[70:73]
	v_mfma_f32_16x16x32_bf16 v[66:69], v[152:155], v[176:179], v[66:69]
	v_mfma_f32_16x16x32_bf16 v[86:89], v[144:147], v[184:187], v[86:89]
	v_mfma_f32_16x16x32_bf16 v[82:85], v[152:155], v[184:187], v[82:85]
	v_mfma_f32_16x16x32_bf16 v[102:105], v[144:147], v[192:195], v[102:105]
	v_mfma_f32_16x16x32_bf16 v[98:101], v[152:155], v[192:195], v[98:101]
	v_mfma_f32_16x16x32_bf16 v[118:121], v[144:147], v[200:203], v[118:121]
	v_mfma_f32_16x16x32_bf16 v[114:117], v[152:155], v[200:203], v[114:117]
	v_mfma_f32_16x16x32_bf16 v[70:73], v[148:151], v[180:183], v[70:73]
	v_mfma_f32_16x16x32_bf16 v[66:69], v[156:159], v[180:183], v[66:69]
	v_mfma_f32_16x16x32_bf16 v[86:89], v[148:151], v[188:191], v[86:89]
	v_mfma_f32_16x16x32_bf16 v[82:85], v[156:159], v[188:191], v[82:85]
	v_mfma_f32_16x16x32_bf16 v[102:105], v[148:151], v[196:199], v[102:105]
	v_mfma_f32_16x16x32_bf16 v[98:101], v[156:159], v[196:199], v[98:101]
	v_mfma_f32_16x16x32_bf16 v[118:121], v[148:151], v[204:207], v[118:121]
	v_mfma_f32_16x16x32_bf16 v[114:117], v[156:159], v[204:207], v[114:117]
	s_setprio 0
	s_setprio 1
	v_mfma_f32_16x16x32_bf16 v[74:77], v[160:163], v[176:179], v[74:77]
	v_mfma_f32_16x16x32_bf16 v[78:81], v[168:171], v[176:179], v[78:81]
	v_mfma_f32_16x16x32_bf16 v[90:93], v[160:163], v[184:187], v[90:93]
	v_mfma_f32_16x16x32_bf16 v[94:97], v[168:171], v[184:187], v[94:97]
	v_mfma_f32_16x16x32_bf16 v[106:109], v[160:163], v[192:195], v[106:109]
	v_mfma_f32_16x16x32_bf16 v[110:113], v[168:171], v[192:195], v[110:113]
	v_mfma_f32_16x16x32_bf16 v[122:125], v[160:163], v[200:203], v[122:125]
	v_mfma_f32_16x16x32_bf16 v[126:129], v[168:171], v[200:203], v[126:129]
	v_mfma_f32_16x16x32_bf16 v[74:77], v[164:167], v[180:183], v[74:77]
	v_mfma_f32_16x16x32_bf16 v[78:81], v[172:175], v[180:183], v[78:81]
	v_mfma_f32_16x16x32_bf16 v[90:93], v[164:167], v[188:191], v[90:93]
	v_mfma_f32_16x16x32_bf16 v[94:97], v[172:175], v[188:191], v[94:97]
	v_mfma_f32_16x16x32_bf16 v[106:109], v[164:167], v[196:199], v[106:109]
	v_mfma_f32_16x16x32_bf16 v[110:113], v[172:175], v[196:199], v[110:113]
	v_mfma_f32_16x16x32_bf16 v[122:125], v[164:167], v[204:207], v[122:125]
	v_mfma_f32_16x16x32_bf16 v[126:129], v[172:175], v[204:207], v[126:129]
	s_setprio 0
	s_barrier
	s_add_i32 s2, 0, 0x18000
	s_add_i32 s81, 0, 0x1c000
	v_add_u32_e32 v156, s2, v138
	v_add_u32_e32 v172, s81, v138
	ds_read_b128 v[144:147], v156
	ds_read_b128 v[148:151], v156 offset:1024
	ds_read_b128 v[152:155], v156 offset:2048
	ds_read_b128 v[156:159], v156 offset:3072
	ds_read_b128 v[160:163], v172
	ds_read_b128 v[164:167], v172 offset:1024
	ds_read_b128 v[168:171], v172 offset:2048
	ds_read_b128 v[172:175], v172 offset:3072
	s_add_u32 s52, s52, 0x40000
	s_addc_u32 s53, s53, 0
	s_mov_b32 m0, s66
	v_lshl_add_u64 v[214:215], s[52:53], 0, v[130:131]
	ds_read_b128 v[176:179], v139 offset:32768
	ds_read_b128 v[180:183], v139 offset:33792
	ds_read_b128 v[184:187], v139 offset:34816
	ds_read_b128 v[188:191], v139 offset:35840
	ds_read_b128 v[192:195], v139 offset:36864
	ds_read_b128 v[196:199], v139 offset:37888
	ds_read_b128 v[200:203], v139 offset:38912
	ds_read_b128 v[204:207], v139 offset:39936
	global_load_lds_dwordx4 v[214:215], off
	v_lshl_add_u64 v[214:215], s[52:53], 0, v[132:133]
	s_mov_b32 m0, s67
	s_nop 0
	global_load_lds_dwordx4 v[214:215], off
	s_waitcnt vmcnt(8)
	s_waitcnt lgkmcnt(0)
	s_barrier
	s_setprio 1
	s_waitcnt lgkmcnt(0)
	v_mfma_f32_16x16x32_bf16 v[2:5], v[144:147], v[176:179], v[2:5]
	v_mfma_f32_16x16x32_bf16 v[6:9], v[152:155], v[176:179], v[6:9]
	v_mfma_f32_16x16x32_bf16 v[22:25], v[144:147], v[184:187], v[22:25]
	v_mfma_f32_16x16x32_bf16 v[18:21], v[152:155], v[184:187], v[18:21]
	v_mfma_f32_16x16x32_bf16 v[38:41], v[144:147], v[192:195], v[38:41]
	v_mfma_f32_16x16x32_bf16 v[34:37], v[152:155], v[192:195], v[34:37]
	v_mfma_f32_16x16x32_bf16 v[54:57], v[144:147], v[200:203], v[54:57]
	v_mfma_f32_16x16x32_bf16 v[50:53], v[152:155], v[200:203], v[50:53]
	v_mfma_f32_16x16x32_bf16 v[2:5], v[148:151], v[180:183], v[2:5]
	v_mfma_f32_16x16x32_bf16 v[6:9], v[156:159], v[180:183], v[6:9]
	v_mfma_f32_16x16x32_bf16 v[22:25], v[148:151], v[188:191], v[22:25]
	v_mfma_f32_16x16x32_bf16 v[18:21], v[156:159], v[188:191], v[18:21]
	v_mfma_f32_16x16x32_bf16 v[38:41], v[148:151], v[196:199], v[38:41]
	v_mfma_f32_16x16x32_bf16 v[34:37], v[156:159], v[196:199], v[34:37]
	v_mfma_f32_16x16x32_bf16 v[54:57], v[148:151], v[204:207], v[54:57]
	v_mfma_f32_16x16x32_bf16 v[50:53], v[156:159], v[204:207], v[50:53]
	s_setprio 0
	s_setprio 1
	v_mfma_f32_16x16x32_bf16 v[10:13], v[160:163], v[176:179], v[10:13]
	v_mfma_f32_16x16x32_bf16 v[14:17], v[168:171], v[176:179], v[14:17]
	v_mfma_f32_16x16x32_bf16 v[26:29], v[160:163], v[184:187], v[26:29]
	v_mfma_f32_16x16x32_bf16 v[30:33], v[168:171], v[184:187], v[30:33]
	v_mfma_f32_16x16x32_bf16 v[42:45], v[160:163], v[192:195], v[42:45]
	v_mfma_f32_16x16x32_bf16 v[46:49], v[168:171], v[192:195], v[46:49]
	v_mfma_f32_16x16x32_bf16 v[58:61], v[160:163], v[200:203], v[58:61]
	v_mfma_f32_16x16x32_bf16 v[62:65], v[168:171], v[200:203], v[62:65]
	v_mfma_f32_16x16x32_bf16 v[10:13], v[164:167], v[180:183], v[10:13]
	v_mfma_f32_16x16x32_bf16 v[14:17], v[172:175], v[180:183], v[14:17]
	v_mfma_f32_16x16x32_bf16 v[26:29], v[164:167], v[188:191], v[26:29]
	v_mfma_f32_16x16x32_bf16 v[30:33], v[172:175], v[188:191], v[30:33]
	v_mfma_f32_16x16x32_bf16 v[42:45], v[164:167], v[196:199], v[42:45]
	v_mfma_f32_16x16x32_bf16 v[46:49], v[172:175], v[196:199], v[46:49]
	v_mfma_f32_16x16x32_bf16 v[58:61], v[164:167], v[204:207], v[58:61]
	v_mfma_f32_16x16x32_bf16 v[62:65], v[172:175], v[204:207], v[62:65]
	s_setprio 0
	s_barrier
; #define PG8_STAGE(bufoff, gbase, voff) do { _Pragma("unroll") for (int _i = 0; _i < 2; ++_i) \
;         __builtin_amdgcn_global_load_lds((const unsigned*)((const char*)(gbase) + (voff)[_i]), (PG8_LAS unsigned*)(lds + (bufoff) + ldsw + _i * 8192), 16, 0, 0); } while (0)
; #define PG8_LDA(dst, b, h) do { _Pragma("unroll") for (int m = 0; m < 4; ++m) _Pragma("unroll") for (int k = 0; k < 2; ++k) dst[m][k] = *(const PG8_LAS bf16x8*)(lds + PG8_SA(b, h) + aoff + m * 2048 + k * 1024); } while (0)
; #define PG8_LDB(dst, b, h) do { _Pragma("unroll") for (int n = 0; n < 2; ++n) _Pragma("unroll") for (int k = 0; k < 2; ++k) dst[n][k] = *(const PG8_LAS bf16x8*)(lds + PG8_SB(b, h) + boff + n * 2048 + k * 1024); } while (0)
; #define PG8_MMA(ai, bj, At, Bt) do { __builtin_amdgcn_s_setprio(1); _Pragma("unroll") for (int m = 0; m < 4; ++m) _Pragma("unroll") for (int n = 0; n < 2; ++n) _Pragma("unroll") for (int k = 0; k < 2; ++k) \
;         acc[ai][bj][m][n] = __builtin_amdgcn_mfma_f32_16x16x32_bf16(Bt[n][k], At[m][k], acc[ai][bj][m][n], 0, 0, 0); __builtin_amdgcn_s_setprio(0); } while (0)
; #define PG8_WAIT_V(n) asm volatile("s_waitcnt vmcnt(" #n ")" ::: "memory")
; #define PG8_WAIT_L(n) asm volatile("s_waitcnt lgkmcnt(" #n ")" ::: "memory")
; #define PG8_BAR __builtin_amdgcn_s_barrier()
;     __device__ __forceinline__ void init(f32x4 (&acc)[2][2][4][2], const Unit& u, int wr, int wc, int fr, int fq) const {
;     ...
;             for (int m = 0; m < 4; ++m) { const size_t off = ((size_t)u.pm * 256 + 128 * ai + 64 * wr + 16 * m + fr) * DM + u.pn * 256 + 32 * wc + 4 * fq;
; #pragma unroll
;                 for (int bj = 0; bj < 2; ++bj)
; #pragma unroll
;                     for (int n = 0; n < 2; ++n) acc[ai][bj][m][n] = __builtin_nontemporal_load((const f32x4*)(x + off + bj * HALF + n * 16)); }
; template <class Epi, class Sched, bool ALIGN_EPI = false, bool SP2 = false>
; __device__ __forceinline__ void gemm_phase(PG8_LAS unsigned char* lds, const Gemm g, const Sched& S, const Epi& E) {
;     ...
;             PG8_LDB(B0, 1, 0); PG8_LDB(B1, 1, 1); PG8_SCHED; PG8_LDA(At, 1, 0); PG8_STAGE(PG8_SA(0, 1), a2 + hstep, voffA);
;             PG8_WAIT_V(8); PG8_WAIT_L(0); PG8_BAR; PG8_MMA(0, 0, At, B0); PG8_MMA(0, 1, At, B1); PG8_BAR; PG8_SCHED;
;             PG8_LDA(At, 1, 1); PG8_STAGE(PG8_SB(1, 0), b3, voffB); PG8_STAGE(PG8_SB(1, 1), b3 + hstep, voffB); PG8_STAGE(PG8_SA(1, 0), a3, voffA);
	s_add_i32 s2, s2, s57
	v_lshl_add_u64 v[140:141], v[140:141], 0, s[26:27]
	s_mov_b32 m0, s2
	ds_read_b128 v[176:179], v139 offset:49152
	ds_read_b128 v[180:183], v139 offset:50176
	ds_read_b128 v[184:187], v139 offset:51200
	ds_read_b128 v[188:191], v139 offset:52224
	ds_read_b128 v[192:195], v139 offset:53248
	ds_read_b128 v[196:199], v139 offset:54272
	ds_read_b128 v[200:203], v139 offset:55296
	ds_read_b128 v[204:207], v139 offset:56320
	global_load_lds_dwordx4 v[140:141], off
	s_add_i32 m0, s2, 0x2000
	s_add_u32 s46, s46, 0x40080
	v_lshl_add_u64 v[140:141], v[208:209], 0, s[26:27]
	s_addc_u32 s47, s47, 0
	s_add_i32 s2, s81, s57
	global_load_lds_dwordx4 v[140:141], off
	v_lshl_add_u64 v[140:141], s[46:47], 0, v[130:131]
	s_mov_b32 m0, s2
	s_nop 0
	global_load_lds_dwordx4 v[140:141], off
	v_lshl_add_u64 v[140:141], s[46:47], 0, v[132:133]
	s_add_i32 m0, s2, 0x2000
	s_nop 0
	global_load_lds_dwordx4 v[140:141], off
	v_lshl_add_u64 v[140:141], v[210:211], 0, s[26:27]
	s_mov_b32 m0, s68
	s_nop 0
	global_load_lds_dwordx4 v[140:141], off
	v_lshl_add_u64 v[140:141], v[212:213], 0, s[26:27]
	s_mov_b32 m0, s69
	s_nop 0
	global_load_lds_dwordx4 v[140:141], off
	s_cmp_lt_i32 s80, 6
	s_cbranch_scc0 .Lxa_hi
	s_cmp_lt_i32 s80, 2
	s_cbranch_scc0 .Lxa_23
	s_cmp_lt_i32 s80, 0
	s_cbranch_scc0 .Lxa_1
	v_add_f32_e32 v2, v2, v216
	v_add_f32_e32 v3, v3, v217
	v_add_f32_e32 v4, v4, v218
	v_add_f32_e32 v5, v5, v219
	v_add_f32_e32 v6, v6, v220
	v_add_f32_e32 v7, v7, v221
	v_add_f32_e32 v8, v8, v222
	v_add_f32_e32 v9, v9, v223
	v_add_f32_e32 v10, v10, v224
	v_add_f32_e32 v11, v11, v225
	v_add_f32_e32 v12, v12, v226
	v_add_f32_e32 v13, v13, v227
	v_add_f32_e32 v14, v14, v228
	v_add_f32_e32 v15, v15, v229
	v_add_f32_e32 v16, v16, v230
	v_add_f32_e32 v17, v17, v231
	s_branch .Lxa_done
.Lxa_1:
	v_add_f32_e32 v22, v22, v216
	v_add_f32_e32 v23, v23, v217
	v_add_f32_e32 v24, v24, v218
	v_add_f32_e32 v25, v25, v219
	v_add_f32_e32 v18, v18, v220
	v_add_f32_e32 v19, v19, v221
	v_add_f32_e32 v20, v20, v222
	v_add_f32_e32 v21, v21, v223
	v_add_f32_e32 v26, v26, v224
	v_add_f32_e32 v27, v27, v225
	v_add_f32_e32 v28, v28, v226
	v_add_f32_e32 v29, v29, v227
	v_add_f32_e32 v30, v30, v228
	v_add_f32_e32 v31, v31, v229
	v_add_f32_e32 v32, v32, v230
	v_add_f32_e32 v33, v33, v231
	s_branch .Lxa_done
.Lxa_23:
	s_cmp_lt_i32 s80, 4
	s_cbranch_scc0 .Lxa_3
	v_add_f32_e32 v38, v38, v216
	v_add_f32_e32 v39, v39, v217
	v_add_f32_e32 v40, v40, v218
	v_add_f32_e32 v41, v41, v219
	v_add_f32_e32 v34, v34, v220
	v_add_f32_e32 v35, v35, v221
	v_add_f32_e32 v36, v36, v222
	v_add_f32_e32 v37, v37, v223
	v_add_f32_e32 v42, v42, v224
	v_add_f32_e32 v43, v43, v225
	v_add_f32_e32 v44, v44, v226
	v_add_f32_e32 v45, v45, v227
	v_add_f32_e32 v46, v46, v228
	v_add_f32_e32 v47, v47, v229
	v_add_f32_e32 v48, v48, v230
	v_add_f32_e32 v49, v49, v231
	s_branch .Lxa_done
.Lxa_3:
	v_add_f32_e32 v54, v54, v216
	v_add_f32_e32 v55, v55, v217
	v_add_f32_e32 v56, v56, v218
	v_add_f32_e32 v57, v57, v219
	v_add_f32_e32 v50, v50, v220
	v_add_f32_e32 v51, v51, v221
	v_add_f32_e32 v52, v52, v222
	v_add_f32_e32 v53, v53, v223
	v_add_f32_e32 v58, v58, v224
	v_add_f32_e32 v59, v59, v225
	v_add_f32_e32 v60, v60, v226
	v_add_f32_e32 v61, v61, v227
	v_add_f32_e32 v62, v62, v228
	v_add_f32_e32 v63, v63, v229
	v_add_f32_e32 v64, v64, v230
	v_add_f32_e32 v65, v65, v231
	s_branch .Lxa_done
.Lxa_hi:
	s_cmp_lt_i32 s80, 10
	s_cbranch_scc0 .Lxa_67
	s_cmp_lt_i32 s80, 8
	s_cbranch_scc0 .Lxa_5
	v_add_f32_e32 v70, v70, v216
	v_add_f32_e32 v71, v71, v217
	v_add_f32_e32 v72, v72, v218
	v_add_f32_e32 v73, v73, v219
	v_add_f32_e32 v66, v66, v220
	v_add_f32_e32 v67, v67, v221
	v_add_f32_e32 v68, v68, v222
	v_add_f32_e32 v69, v69, v223
	v_add_f32_e32 v74, v74, v224
	v_add_f32_e32 v75, v75, v225
	v_add_f32_e32 v76, v76, v226
	v_add_f32_e32 v77, v77, v227
	v_add_f32_e32 v78, v78, v228
	v_add_f32_e32 v79, v79, v229
	v_add_f32_e32 v80, v80, v230
	v_add_f32_e32 v81, v81, v231
	s_branch .Lxa_done
.Lxa_5:
	v_add_f32_e32 v86, v86, v216
	v_add_f32_e32 v87, v87, v217
	v_add_f32_e32 v88, v88, v218
	v_add_f32_e32 v89, v89, v219
	v_add_f32_e32 v82, v82, v220
	v_add_f32_e32 v83, v83, v221
	v_add_f32_e32 v84, v84, v222
	v_add_f32_e32 v85, v85, v223
	v_add_f32_e32 v90, v90, v224
	v_add_f32_e32 v91, v91, v225
	v_add_f32_e32 v92, v92, v226
	v_add_f32_e32 v93, v93, v227
	v_add_f32_e32 v94, v94, v228
	v_add_f32_e32 v95, v95, v229
	v_add_f32_e32 v96, v96, v230
	v_add_f32_e32 v97, v97, v231
	s_branch .Lxa_done
.Lxa_67:
	s_cmp_lt_i32 s80, 12
	s_cbranch_scc0 .Lxa_7
	v_add_f32_e32 v102, v102, v216
	v_add_f32_e32 v103, v103, v217
	v_add_f32_e32 v104, v104, v218
	v_add_f32_e32 v105, v105, v219
	v_add_f32_e32 v98, v98, v220
	v_add_f32_e32 v99, v99, v221
	v_add_f32_e32 v100, v100, v222
	v_add_f32_e32 v101, v101, v223
	v_add_f32_e32 v106, v106, v224
	v_add_f32_e32 v107, v107, v225
	v_add_f32_e32 v108, v108, v226
	v_add_f32_e32 v109, v109, v227
	v_add_f32_e32 v110, v110, v228
	v_add_f32_e32 v111, v111, v229
	v_add_f32_e32 v112, v112, v230
	v_add_f32_e32 v113, v113, v231
	s_branch .Lxa_done
.Lxa_7:
	v_add_f32_e32 v118, v118, v216
	v_add_f32_e32 v119, v119, v217
	v_add_f32_e32 v120, v120, v218
	v_add_f32_e32 v121, v121, v219
	v_add_f32_e32 v114, v114, v220
	v_add_f32_e32 v115, v115, v221
	v_add_f32_e32 v116, v116, v222
	v_add_f32_e32 v117, v117, v223
	v_add_f32_e32 v122, v122, v224
	v_add_f32_e32 v123, v123, v225
	v_add_f32_e32 v124, v124, v226
	v_add_f32_e32 v125, v125, v227
	v_add_f32_e32 v126, v126, v228
	v_add_f32_e32 v127, v127, v229
	v_add_f32_e32 v128, v128, v230
	v_add_f32_e32 v129, v129, v231
; #define PG8_STAGE(bufoff, gbase, voff) do { _Pragma("unroll") for (int _i = 0; _i < 2; ++_i) \
;         __builtin_amdgcn_global_load_lds((const unsigned*)((const char*)(gbase) + (voff)[_i]), (PG8_LAS unsigned*)(lds + (bufoff) + ldsw + _i * 8192), 16, 0, 0); } while (0)
; #define PG8_LDA(dst, b, h) do { _Pragma("unroll") for (int m = 0; m < 4; ++m) _Pragma("unroll") for (int k = 0; k < 2; ++k) dst[m][k] = *(const PG8_LAS bf16x8*)(lds + PG8_SA(b, h) + aoff + m * 2048 + k * 1024); } while (0)
; #define PG8_MMA(ai, bj, At, Bt) do { __builtin_amdgcn_s_setprio(1); _Pragma("unroll") for (int m = 0; m < 4; ++m) _Pragma("unroll") for (int n = 0; n < 2; ++n) _Pragma("unroll") for (int k = 0; k < 2; ++k) \
;         acc[ai][bj][m][n] = __builtin_amdgcn_mfma_f32_16x16x32_bf16(Bt[n][k], At[m][k], acc[ai][bj][m][n], 0, 0, 0); __builtin_amdgcn_s_setprio(0); } while (0)
; #define PG8_WAIT_V(n) asm volatile("s_waitcnt vmcnt(" #n ")" ::: "memory")
; #define PG8_WAIT_L(n) asm volatile("s_waitcnt lgkmcnt(" #n ")" ::: "memory")
; #define PG8_BAR __builtin_amdgcn_s_barrier()
; #define PG8_SCHED __builtin_amdgcn_sched_barrier(0)
;     __device__ __forceinline__ void init(f32x4 (&acc)[2][2][4][2], const Unit& u, int wr, int wc, int fr, int fq) const {
;     ...
;             for (int m = 0; m < 4; ++m) { const size_t off = ((size_t)u.pm * 256 + 128 * ai + 64 * wr + 16 * m + fr) * DM + u.pn * 256 + 32 * wc + 4 * fq;
; #pragma unroll
;                 for (int bj = 0; bj < 2; ++bj)
; #pragma unroll
;                     for (int n = 0; n < 2; ++n) acc[ai][bj][m][n] = __builtin_nontemporal_load((const f32x4*)(x + off + bj * HALF + n * 16)); }
; template <class Epi, class Sched, bool ALIGN_EPI = false, bool SP2 = false>
; __device__ __forceinline__ void gemm_phase(PG8_LAS unsigned char* lds, const Gemm g, const Sched& S, const Epi& E) {
;     ...
;             PG8_LDA(At, 1, 1); PG8_STAGE(PG8_SB(1, 0), b3, voffB); PG8_STAGE(PG8_SB(1, 1), b3 + hstep, voffB); PG8_STAGE(PG8_SA(1, 0), a3, voffA);
;             PG8_WAIT_V(8); PG8_WAIT_L(0); PG8_BAR; PG8_MMA(1, 0, At, B0); PG8_MMA(1, 1, At, B1); PG8_BAR; PG8_SCHED;
.Lxa_done:
	s_add_i32 s92, s80, 4
	s_and_b32 s93, s92, 6
	s_lshl_b32 s93, s93, 15
	s_and_b32 s92, s92, 8
	s_lshl_b32 s92, s92, 16
	s_add_i32 s92, s92, s93
	s_cmp_eq_u32 s80, 12
	s_cselect_b32 s90, s86, s84
	s_cselect_b32 s91, s87, s85
	s_add_u32 s90, s90, s92
	s_addc_u32 s91, s91, 0
	v_lshl_add_u64 v[232:233], v[234:235], 0, s[90:91]
	global_load_dwordx4 v[216:219], v[232:233], off nt
	global_load_dwordx4 v[220:223], v[232:233], off offset:64 nt
	global_load_dwordx4 v[224:227], v[232:233], off offset:512 nt
	global_load_dwordx4 v[228:231], v[232:233], off offset:576 nt
	s_waitcnt vmcnt(12)
	s_waitcnt lgkmcnt(0)
	s_barrier
	s_setprio 1
	s_waitcnt lgkmcnt(0)
	v_mfma_f32_16x16x32_bf16 v[70:73], v[144:147], v[176:179], v[70:73]
	v_mfma_f32_16x16x32_bf16 v[66:69], v[152:155], v[176:179], v[66:69]
	v_mfma_f32_16x16x32_bf16 v[86:89], v[144:147], v[184:187], v[86:89]
	v_mfma_f32_16x16x32_bf16 v[82:85], v[152:155], v[184:187], v[82:85]
	v_mfma_f32_16x16x32_bf16 v[102:105], v[144:147], v[192:195], v[102:105]
	v_mfma_f32_16x16x32_bf16 v[98:101], v[152:155], v[192:195], v[98:101]
	v_mfma_f32_16x16x32_bf16 v[118:121], v[144:147], v[200:203], v[118:121]
	v_mfma_f32_16x16x32_bf16 v[114:117], v[152:155], v[200:203], v[114:117]
	v_mfma_f32_16x16x32_bf16 v[70:73], v[148:151], v[180:183], v[70:73]
	v_mfma_f32_16x16x32_bf16 v[66:69], v[156:159], v[180:183], v[66:69]
	v_mfma_f32_16x16x32_bf16 v[86:89], v[148:151], v[188:191], v[86:89]
	v_mfma_f32_16x16x32_bf16 v[82:85], v[156:159], v[188:191], v[82:85]
	v_mfma_f32_16x16x32_bf16 v[102:105], v[148:151], v[196:199], v[102:105]
	v_mfma_f32_16x16x32_bf16 v[98:101], v[156:159], v[196:199], v[98:101]
	v_mfma_f32_16x16x32_bf16 v[118:121], v[148:151], v[204:207], v[118:121]
	v_mfma_f32_16x16x32_bf16 v[114:117], v[156:159], v[204:207], v[114:117]
	s_setprio 0
	s_setprio 1
	v_mfma_f32_16x16x32_bf16 v[74:77], v[160:163], v[176:179], v[74:77]
	v_mfma_f32_16x16x32_bf16 v[78:81], v[168:171], v[176:179], v[78:81]
	v_mfma_f32_16x16x32_bf16 v[90:93], v[160:163], v[184:187], v[90:93]
	v_mfma_f32_16x16x32_bf16 v[94:97], v[168:171], v[184:187], v[94:97]
	v_mfma_f32_16x16x32_bf16 v[106:109], v[160:163], v[192:195], v[106:109]
	v_mfma_f32_16x16x32_bf16 v[110:113], v[168:171], v[192:195], v[110:113]
	v_mfma_f32_16x16x32_bf16 v[122:125], v[160:163], v[200:203], v[122:125]
	v_mfma_f32_16x16x32_bf16 v[126:129], v[168:171], v[200:203], v[126:129]
	v_mfma_f32_16x16x32_bf16 v[74:77], v[164:167], v[180:183], v[74:77]
	v_mfma_f32_16x16x32_bf16 v[78:81], v[172:175], v[180:183], v[78:81]
	v_mfma_f32_16x16x32_bf16 v[90:93], v[164:167], v[188:191], v[90:93]
	v_mfma_f32_16x16x32_bf16 v[94:97], v[172:175], v[188:191], v[94:97]
	v_mfma_f32_16x16x32_bf16 v[106:109], v[164:167], v[196:199], v[106:109]
	v_mfma_f32_16x16x32_bf16 v[110:113], v[172:175], v[196:199], v[110:113]
	v_mfma_f32_16x16x32_bf16 v[122:125], v[164:167], v[204:207], v[122:125]
	v_mfma_f32_16x16x32_bf16 v[126:129], v[172:175], v[204:207], v[126:129]
	s_setprio 0
	s_barrier
	s_add_i32 s80, s80, 2
	s_add_u32 s48, s48, 0x100
	s_addc_u32 s49, s49, 0
	s_add_u32 s78, s78, 0x100
	s_addc_u32 s79, s79, 0
	s_cmp_gt_u32 s80, 13
	s_cbranch_scc0 .LBB0_722
	s_and_b64 vcc, exec, s[34:35]
	s_cbranch_vccz .LBB0_725
	s_barrier
;     __device__ __forceinline__ void operator()(f32x4 (&acc)[2][2][4][2], const Unit& u, int wr, int wc, int fr, int fq) const {
;         asm volatile("" : "+v"(fr)); asm volatile("" : "+v"(fq));
; #pragma unroll
;         for (int ai = 0; ai < 2; ++ai)
; #pragma unroll
;             for (int m = 0; m < 4; ++m) { const size_t off = ((size_t)u.pm * 256 + 128 * ai + 64 * wr + 16 * m + fr) * DM + u.pn * 256 + 32 * wc + 4 * fq;
; #pragma unroll
;                 for (int bj = 0; bj < 2; ++bj)
; #pragma unroll
;                     for (int n = 0; n < 2; ++n) *(f32x4*)(out + off + bj * HALF + n * 16) = acc[ai][bj][m][n]; }
;     }
; template <class Epi, class Sched, bool ALIGN_EPI = false, bool SP2 = false>
; __device__ __forceinline__ void gemm_phase(PG8_LAS unsigned char* lds, const Gemm g, const Sched& S, const Epi& E) {
;     ...
; #pragma unroll
;         for (int a = 0; a < 2; ++a)
; #pragma unroll
;             for (int b = 0; b < 2; ++b)
; #pragma unroll
;                 for (int m = 0; m < 4; ++m)
; #pragma unroll
;                     for (int n = 0; n < 2; ++n) acc[a][b][m][n] = (f32x4){0.f, 0.f, 0.f, 0.f};
;         if constexpr (Epi::HAS_INIT) E.init(acc, nxt, wr, wc, fr, fq);
.LBB0_725:
	s_ashr_i32 s31, s30, 31
	s_lshl_b64 s[30:31], s[30:31], 8
	v_mov_b32_e32 v140, v142
	s_add_u32 s30, s30, s4
	s_addc_u32 s31, s31, 0
	v_ashrrev_i32_e32 v141, 31, v140
	v_lshl_add_u64 v[140:141], s[30:31], 0, v[140:141]
	v_mov_b32_e32 v144, v143
	s_lshl_b32 s28, s28, 8
	v_lshlrev_b64 v[140:141], 12, v[140:141]
	s_ashr_i32 s29, s28, 31
	v_lshl_add_u64 v[140:141], s[50:51], 0, v[140:141]
	v_lshlrev_b32_e32 v144, 2, v144
	v_lshl_add_u64 v[140:141], s[28:29], 2, v[140:141]
	v_ashrrev_i32_e32 v145, 31, v144
	v_lshl_add_u64 v[140:141], v[140:141], 0, s[6:7]
	v_lshl_add_u64 v[140:141], v[144:145], 2, v[140:141]
	global_store_dwordx4 v[140:141], v[2:5], off
	global_store_dwordx4 v[140:141], v[6:9], off offset:64
	global_store_dwordx4 v[140:141], v[10:13], off offset:512
	global_store_dwordx4 v[140:141], v[14:17], off offset:576
	v_add_co_u32_e32 v4, vcc, s58, v140
	v_lshl_add_u64 v[2:3], v[140:141], 0, s[8:9]
	s_nop 0
	v_addc_co_u32_e32 v5, vcc, 0, v141, vcc
	global_store_dwordx4 v[4:5], v[22:25], off
	global_store_dwordx4 v[2:3], v[18:21], off offset:64
	global_store_dwordx4 v[2:3], v[26:29], off offset:512
	global_store_dwordx4 v[2:3], v[30:33], off offset:576
	v_add_co_u32_e32 v4, vcc, s59, v140
	v_lshl_add_u64 v[2:3], v[140:141], 0, s[10:11]
	s_nop 0
	v_addc_co_u32_e32 v5, vcc, 0, v141, vcc
	global_store_dwordx4 v[4:5], v[38:41], off
	global_store_dwordx4 v[2:3], v[34:37], off offset:64
	global_store_dwordx4 v[2:3], v[42:45], off offset:512
	global_store_dwordx4 v[2:3], v[46:49], off offset:576
	v_add_co_u32_e32 v4, vcc, s60, v140
	v_lshl_add_u64 v[2:3], v[140:141], 0, s[12:13]
	s_nop 0
	v_addc_co_u32_e32 v5, vcc, 0, v141, vcc
	global_store_dwordx4 v[4:5], v[54:57], off
	global_store_dwordx4 v[2:3], v[50:53], off offset:64
	global_store_dwordx4 v[2:3], v[58:61], off offset:512
	global_store_dwordx4 v[2:3], v[62:65], off offset:576
	v_add_co_u32_e32 v4, vcc, s61, v140
	v_lshl_add_u64 v[2:3], v[140:141], 0, s[14:15]
	s_nop 0
	v_addc_co_u32_e32 v5, vcc, 0, v141, vcc
	global_store_dwordx4 v[4:5], v[70:73], off
	global_store_dwordx4 v[2:3], v[66:69], off offset:64
	global_store_dwordx4 v[2:3], v[74:77], off offset:512
	global_store_dwordx4 v[2:3], v[78:81], off offset:576
	v_add_co_u32_e32 v4, vcc, s62, v140
	v_lshl_add_u64 v[2:3], v[140:141], 0, s[18:19]
	s_nop 0
	v_addc_co_u32_e32 v5, vcc, 0, v141, vcc
	global_store_dwordx4 v[4:5], v[86:89], off
	global_store_dwordx4 v[2:3], v[82:85], off offset:64
	global_store_dwordx4 v[2:3], v[90:93], off offset:512
	global_store_dwordx4 v[2:3], v[94:97], off offset:576
	v_add_co_u32_e32 v4, vcc, s63, v140
	v_lshl_add_u64 v[2:3], v[140:141], 0, s[20:21]
	s_nop 0
	v_addc_co_u32_e32 v5, vcc, 0, v141, vcc
	global_store_dwordx4 v[4:5], v[102:105], off
	global_store_dwordx4 v[2:3], v[98:101], off offset:64
	global_store_dwordx4 v[2:3], v[106:109], off offset:512
	global_store_dwordx4 v[2:3], v[110:113], off offset:576
	v_add_co_u32_e32 v4, vcc, 0xb0000, v140
	v_lshl_add_u64 v[2:3], v[140:141], 0, s[22:23]
	s_nop 0
	v_addc_co_u32_e32 v5, vcc, 0, v141, vcc
	s_andn2_b64 vcc, exec, s[44:45]
	s_mov_b64 s[28:29], -1
	global_store_dwordx4 v[4:5], v[118:121], off
	global_store_dwordx4 v[2:3], v[114:117], off offset:64
	global_store_dwordx4 v[2:3], v[122:125], off offset:512
	global_store_dwordx4 v[2:3], v[126:129], off offset:576
	s_cbranch_vccnz .LBB0_709
	v_mov_b64_e32 v[2:3], 0
	v_mov_b64_e32 v[4:5], 0
	v_mov_b64_e32 v[6:7], 0
	v_mov_b64_e32 v[8:9], 0
	v_mov_b64_e32 v[10:11], 0
	v_mov_b64_e32 v[12:13], 0
	v_mov_b64_e32 v[14:15], 0
	v_mov_b64_e32 v[16:17], 0
	v_mov_b64_e32 v[18:19], 0
	v_mov_b64_e32 v[20:21], 0
	v_mov_b64_e32 v[22:23], 0
	v_mov_b64_e32 v[24:25], 0
	v_mov_b64_e32 v[26:27], 0
	v_mov_b64_e32 v[28:29], 0
	v_mov_b64_e32 v[30:31], 0
	v_mov_b64_e32 v[32:33], 0
	v_mov_b64_e32 v[34:35], 0
	v_mov_b64_e32 v[36:37], 0
	v_mov_b64_e32 v[38:39], 0
	v_mov_b64_e32 v[40:41], 0
	v_mov_b64_e32 v[42:43], 0
	v_mov_b64_e32 v[44:45], 0
	v_mov_b64_e32 v[46:47], 0
	v_mov_b64_e32 v[48:49], 0
	v_mov_b64_e32 v[50:51], 0
	v_mov_b64_e32 v[52:53], 0
	v_mov_b64_e32 v[54:55], 0
	v_mov_b64_e32 v[56:57], 0
	v_mov_b64_e32 v[58:59], 0
	v_mov_b64_e32 v[60:61], 0
	v_mov_b64_e32 v[62:63], 0
	v_mov_b64_e32 v[64:65], 0
	v_mov_b64_e32 v[66:67], 0
	v_mov_b64_e32 v[68:69], 0
	v_mov_b64_e32 v[70:71], 0
	v_mov_b64_e32 v[72:73], 0
	v_mov_b64_e32 v[74:75], 0
	v_mov_b64_e32 v[76:77], 0
	v_mov_b64_e32 v[78:79], 0
	v_mov_b64_e32 v[80:81], 0
	v_mov_b64_e32 v[82:83], 0
	v_mov_b64_e32 v[84:85], 0
	v_mov_b64_e32 v[86:87], 0
	v_mov_b64_e32 v[88:89], 0
	v_mov_b64_e32 v[90:91], 0
	v_mov_b64_e32 v[92:93], 0
	v_mov_b64_e32 v[94:95], 0
	v_mov_b64_e32 v[96:97], 0
	v_mov_b64_e32 v[98:99], 0
	v_mov_b64_e32 v[100:101], 0
	v_mov_b64_e32 v[102:103], 0
	v_mov_b64_e32 v[104:105], 0
	v_mov_b64_e32 v[106:107], 0
	v_mov_b64_e32 v[108:109], 0
	v_mov_b64_e32 v[110:111], 0
	v_mov_b64_e32 v[112:113], 0
	v_mov_b64_e32 v[114:115], 0
	v_mov_b64_e32 v[116:117], 0
	v_mov_b64_e32 v[118:119], 0
	v_mov_b64_e32 v[120:121], 0
	v_mov_b64_e32 v[122:123], 0
	v_mov_b64_e32 v[124:125], 0
	v_mov_b64_e32 v[126:127], 0
	v_mov_b64_e32 v[128:129], 0
	s_andn2_b64 vcc, exec, s[24:25]
	s_cbranch_vccnz .LBB0_708
	s_barrier
	s_branch .LBB0_708
